# scan: hand-written consumer (reassociated state update, no nops) + hand-written producer (4 waves, efficient y flush, prefetch waits moved)
# speedup vs baseline: 1.0315x; 1.0315x over previous
; #define LAS __attribute__((address_space(3)))
; DI void rwkv_scan_phase(int wv, const Params& P, LAS unsigned char* lds) {
;     ...
;             const int cg = lane & 15, rloc = wave * 4 + (lane >> 4);
;             f32x4 S = (f32x4){0.f, 0.f, 0.f, 0.f};
;             __syncthreads();
;             __builtin_amdgcn_s_setprio(3);
; #pragma unroll 1
;             for (int ck = 0; ck < nck; ++ck) { const int buf = ck & 1;
;                 const LAS float* sb = stg + buf * RW_T * 5 * 64 + 4 * cg; const LAS float* vb = vst + buf * RW_T * 8 + rloc; LAS float* yb = ybuf + buf * RW_T * 128 + wave * 64 + lane;
;                 const unsigned sba = (unsigned)(size_t)sb, vba = (unsigned)(size_t)vb;
;                 f32x4 nkA, ddA, bbA, kpA, rrA, nkB, ddB, bbB, kpB, rrB; float vvA, vvB;
;     ...
;                 f32x2 yacc = (f32x2){0.f, 0.f};
;                 unsigned sbt = sba, vbt = vba; LAS float* ybt = yb;
;                 RW_LDS_LOAD(A, 0); RW_LDS_WAIT(A);
; #pragma unroll 1
;                 for (int tt = 0; tt < RW_T; tt += 16) { sbt = sba + (unsigned)tt * 1280u; vbt = vba + (unsigned)tt * 32u; ybt = yb + tt * 128;
;                     RW_LDS_LOAD(B, 1); RW_STEP(A, 0); RW_LDS_WAIT(B);
;                     RW_LDS_LOAD(A, 2); RW_STEP(B, 1); RW_LDS_WAIT(A);
;                     RW_LDS_LOAD(B, 3); RW_STEP(A, 2); RW_LDS_WAIT(B);
;                     RW_LDS_LOAD(A, 4); RW_STEP(B, 3); RW_LDS_WAIT(A);
;                     RW_LDS_LOAD(B, 5); RW_STEP(A, 4); RW_LDS_WAIT(B);
;                     RW_LDS_LOAD(A, 6); RW_STEP(B, 5); RW_LDS_WAIT(A);
;                     RW_LDS_LOAD(B, 7); RW_STEP(A, 6); RW_LDS_WAIT(B);
;                     RW_LDS_LOAD(A, 8); RW_STEP(B, 7); RW_LDS_WAIT(A);
;                     RW_LDS_LOAD(B, 9); RW_STEP(A, 8); RW_LDS_WAIT(B);
;                     RW_LDS_LOAD(A, 10); RW_STEP(B, 9); RW_LDS_WAIT(A);
;                     RW_LDS_LOAD(B, 11); RW_STEP(A, 10); RW_LDS_WAIT(B);
;                     RW_LDS_LOAD(A, 12); RW_STEP(B, 11); RW_LDS_WAIT(A);
;                     RW_LDS_LOAD(B, 13); RW_STEP(A, 12); RW_LDS_WAIT(B);
;                     RW_LDS_LOAD(A, 14); RW_STEP(B, 13); RW_LDS_WAIT(A);
;                     RW_LDS_LOAD(B, 15); RW_STEP(A, 14); RW_LDS_WAIT(B);
;                     RW_LDS_LOAD(A, 16); RW_STEP(B, 15); RW_LDS_WAIT(A);
;                 }
;                 yb[(RW_T - 1) * 128] = yacc[0] + yacc[1];
.LBB0_3177:
	s_waitcnt lgkmcnt(0)
	s_barrier
	s_and_saveexec_b64 s[20:21], s[2:3]
	s_xor_b64 s[20:21], exec, s[20:21]
	s_cbranch_execz .LBB0_3185
	s_barrier
	s_setprio 3
	v_mov_b32_e32 v73, 0
	v_mov_b32_e32 v58, 0
	v_mov_b32_e32 v59, 0
	v_mov_b32_e32 v60, 0
	v_mov_b32_e32 v61, 0
	s_mov_b32 s47, 0
.Lscan_chunk:
	s_lshl_b32 s40, s47, 5
	s_and_b32 s40, s40, 32
	s_mul_i32 s41, s40, 0x500
	v_add_u32_e32 v74, s41, v45
	v_lshl_add_u32 v75, s40, 5, v63
	v_lshl_add_u32 v76, s40, 9, v66
	ds_read_b128 v[0:3], v74
	ds_read_b32 v42, v75
	ds_read_b128 v[4:7], v74 offset:256
	ds_read_b128 v[8:11], v74 offset:512
	ds_read_b128 v[12:15], v74 offset:768
	ds_read_b128 v[16:19], v74 offset:1024
	s_waitcnt lgkmcnt(1)
	v_pk_mul_f32 v[0:1], v[58:59], v[0:1]
	ds_read_b128 v[20:23], v74 offset:1280
	v_pk_fma_f32 v[0:1], v[60:61], v[2:3], v[0:1]
	ds_read_b32 v62, v75 offset:32
	v_add_f32_e32 v0, v0, v1
	v_pk_mul_f32 v[12:13], v[12:13], v[42:43] op_sel_hi:[1,0]
	v_pk_mul_f32 v[14:15], v[14:15], v[42:43] op_sel_hi:[1,0]
	v_add_f32_dpp v0, v0, v0 quad_perm:[1,0,3,2] row_mask:0xf bank_mask:0xf bound_ctrl:1
	v_pk_fma_f32 v[12:13], v[58:59], v[4:5], v[12:13]
	v_pk_fma_f32 v[14:15], v[60:61], v[6:7], v[14:15]
	v_add_f32_dpp v0, v0, v0 quad_perm:[2,3,0,1] row_mask:0xf bank_mask:0xf bound_ctrl:1
	ds_read_b128 v[24:27], v74 offset:1536
	ds_read_b128 v[28:31], v74 offset:1792
	v_add_f32_dpp v0, v0, v0 row_half_mirror row_mask:0xf bank_mask:0xf bound_ctrl:1
	ds_read_b128 v[32:35], v74 offset:2048
	ds_read_b128 v[36:39], v74 offset:2304
	v_add_f32_dpp v0, v0, v0 row_mirror row_mask:0xf bank_mask:0xf bound_ctrl:1
	s_nop 0
	v_pk_fma_f32 v[58:59], v[8:9], v[0:1], v[12:13] op_sel_hi:[1,0,1]
	v_pk_fma_f32 v[60:61], v[10:11], v[0:1], v[14:15] op_sel_hi:[1,0,1]
	s_waitcnt lgkmcnt(1)
	v_pk_mul_f32 v[20:21], v[58:59], v[20:21]
	ds_read_b128 v[0:3], v74 offset:2560
	v_pk_fma_f32 v[20:21], v[60:61], v[22:23], v[20:21]
	ds_read_b32 v42, v75 offset:64
	v_add_f32_e32 v20, v20, v21
	v_pk_mul_f32 v[32:33], v[32:33], v[62:63] op_sel_hi:[1,0]
	v_pk_mul_f32 v[34:35], v[34:35], v[62:63] op_sel_hi:[1,0]
	v_add_f32_dpp v20, v20, v20 quad_perm:[1,0,3,2] row_mask:0xf bank_mask:0xf bound_ctrl:1
	v_pk_fma_f32 v[32:33], v[58:59], v[24:25], v[32:33]
	v_pk_fma_f32 v[34:35], v[60:61], v[26:27], v[34:35]
	v_pk_mul_f32 v[64:65], v[16:17], v[58:59]
	v_add_f32_dpp v20, v20, v20 quad_perm:[2,3,0,1] row_mask:0xf bank_mask:0xf bound_ctrl:1
	v_pk_fma_f32 v[64:65], v[18:19], v[60:61], v[64:65]
	ds_read_b128 v[4:7], v74 offset:2816
	v_add_f32_dpp v20, v20, v20 row_half_mirror row_mask:0xf bank_mask:0xf bound_ctrl:1
	ds_read_b128 v[8:11], v74 offset:3072
	ds_read_b128 v[12:15], v74 offset:3328
	v_add_f32_dpp v20, v20, v20 row_mirror row_mask:0xf bank_mask:0xf bound_ctrl:1
	ds_read_b128 v[16:19], v74 offset:3584
	v_pk_fma_f32 v[58:59], v[28:29], v[20:21], v[32:33] op_sel_hi:[1,0,1]
	v_pk_fma_f32 v[60:61], v[30:31], v[20:21], v[34:35] op_sel_hi:[1,0,1]
	v_add_f32_e32 v64, v64, v65
	ds_write_b32 v76, v64
	s_waitcnt lgkmcnt(2)
	v_pk_mul_f32 v[0:1], v[58:59], v[0:1]
	ds_read_b128 v[20:23], v74 offset:3840
	v_pk_fma_f32 v[0:1], v[60:61], v[2:3], v[0:1]
	ds_read_b32 v62, v75 offset:96
	v_add_f32_e32 v0, v0, v1
	v_pk_mul_f32 v[12:13], v[12:13], v[42:43] op_sel_hi:[1,0]
	v_pk_mul_f32 v[14:15], v[14:15], v[42:43] op_sel_hi:[1,0]
	v_add_f32_dpp v0, v0, v0 quad_perm:[1,0,3,2] row_mask:0xf bank_mask:0xf bound_ctrl:1
	v_pk_fma_f32 v[12:13], v[58:59], v[4:5], v[12:13]
	v_pk_fma_f32 v[14:15], v[60:61], v[6:7], v[14:15]
	v_pk_mul_f32 v[64:65], v[36:37], v[58:59]
	v_add_f32_dpp v0, v0, v0 quad_perm:[2,3,0,1] row_mask:0xf bank_mask:0xf bound_ctrl:1
	v_pk_fma_f32 v[64:65], v[38:39], v[60:61], v[64:65]
	ds_read_b128 v[24:27], v74 offset:4096
	v_add_f32_dpp v0, v0, v0 row_half_mirror row_mask:0xf bank_mask:0xf bound_ctrl:1
	ds_read_b128 v[28:31], v74 offset:4352
	ds_read_b128 v[32:35], v74 offset:4608
	v_add_f32_dpp v0, v0, v0 row_mirror row_mask:0xf bank_mask:0xf bound_ctrl:1
	ds_read_b128 v[36:39], v74 offset:4864
	v_pk_fma_f32 v[58:59], v[8:9], v[0:1], v[12:13] op_sel_hi:[1,0,1]
	v_pk_fma_f32 v[60:61], v[10:11], v[0:1], v[14:15] op_sel_hi:[1,0,1]
	v_add_f32_e32 v64, v64, v65
	ds_write_b32 v76, v64 offset:512
	s_waitcnt lgkmcnt(2)
	v_pk_mul_f32 v[20:21], v[58:59], v[20:21]
	ds_read_b128 v[0:3], v74 offset:5120
	v_pk_fma_f32 v[20:21], v[60:61], v[22:23], v[20:21]
	ds_read_b32 v42, v75 offset:128
	v_add_f32_e32 v20, v20, v21
	v_pk_mul_f32 v[32:33], v[32:33], v[62:63] op_sel_hi:[1,0]
	v_pk_mul_f32 v[34:35], v[34:35], v[62:63] op_sel_hi:[1,0]
	v_add_f32_dpp v20, v20, v20 quad_perm:[1,0,3,2] row_mask:0xf bank_mask:0xf bound_ctrl:1
	v_pk_fma_f32 v[32:33], v[58:59], v[24:25], v[32:33]
	v_pk_fma_f32 v[34:35], v[60:61], v[26:27], v[34:35]
	v_pk_mul_f32 v[64:65], v[16:17], v[58:59]
	v_add_f32_dpp v20, v20, v20 quad_perm:[2,3,0,1] row_mask:0xf bank_mask:0xf bound_ctrl:1
	v_pk_fma_f32 v[64:65], v[18:19], v[60:61], v[64:65]
	ds_read_b128 v[4:7], v74 offset:5376
	v_add_f32_dpp v20, v20, v20 row_half_mirror row_mask:0xf bank_mask:0xf bound_ctrl:1
	ds_read_b128 v[8:11], v74 offset:5632
	ds_read_b128 v[12:15], v74 offset:5888
	v_add_f32_dpp v20, v20, v20 row_mirror row_mask:0xf bank_mask:0xf bound_ctrl:1
	ds_read_b128 v[16:19], v74 offset:6144
	v_pk_fma_f32 v[58:59], v[28:29], v[20:21], v[32:33] op_sel_hi:[1,0,1]
	v_pk_fma_f32 v[60:61], v[30:31], v[20:21], v[34:35] op_sel_hi:[1,0,1]
	v_add_f32_e32 v64, v64, v65
	ds_write_b32 v76, v64 offset:1024
	s_waitcnt lgkmcnt(2)
; #define LAS __attribute__((address_space(3)))
; #define RW_LDS_WAIT(X) asm volatile("s_waitcnt lgkmcnt(0)" : "+v"(nk##X), "+v"(dd##X), "+v"(bb##X), "+v"(kp##X), "+v"(rr##X), "+v"(vv##X) :: "memory")
; DI void rwkv_scan_phase(int wv, const Params& P, LAS unsigned char* lds) {
;     ...
;                 f32x2 yacc = (f32x2){0.f, 0.f};
;                 unsigned sbt = sba, vbt = vba; LAS float* ybt = yb;
;                 RW_LDS_LOAD(A, 0); RW_LDS_WAIT(A);
; #pragma unroll 1
;                 for (int tt = 0; tt < RW_T; tt += 16) { sbt = sba + (unsigned)tt * 1280u; vbt = vba + (unsigned)tt * 32u; ybt = yb + tt * 128;
;                     RW_LDS_LOAD(B, 1); RW_STEP(A, 0); RW_LDS_WAIT(B);
;                     RW_LDS_LOAD(A, 2); RW_STEP(B, 1); RW_LDS_WAIT(A);
;                     RW_LDS_LOAD(B, 3); RW_STEP(A, 2); RW_LDS_WAIT(B);
;                     RW_LDS_LOAD(A, 4); RW_STEP(B, 3); RW_LDS_WAIT(A);
;                     RW_LDS_LOAD(B, 5); RW_STEP(A, 4); RW_LDS_WAIT(B);
;                     RW_LDS_LOAD(A, 6); RW_STEP(B, 5); RW_LDS_WAIT(A);
;                     RW_LDS_LOAD(B, 7); RW_STEP(A, 6); RW_LDS_WAIT(B);
;                     RW_LDS_LOAD(A, 8); RW_STEP(B, 7); RW_LDS_WAIT(A);
;                     RW_LDS_LOAD(B, 9); RW_STEP(A, 8); RW_LDS_WAIT(B);
;                     RW_LDS_LOAD(A, 10); RW_STEP(B, 9); RW_LDS_WAIT(A);
;                     RW_LDS_LOAD(B, 11); RW_STEP(A, 10); RW_LDS_WAIT(B);
;                     RW_LDS_LOAD(A, 12); RW_STEP(B, 11); RW_LDS_WAIT(A);
;                     RW_LDS_LOAD(B, 13); RW_STEP(A, 12); RW_LDS_WAIT(B);
;                     RW_LDS_LOAD(A, 14); RW_STEP(B, 13); RW_LDS_WAIT(A);
;                     RW_LDS_LOAD(B, 15); RW_STEP(A, 14); RW_LDS_WAIT(B);
;                     RW_LDS_LOAD(A, 16); RW_STEP(B, 15); RW_LDS_WAIT(A);
	v_pk_mul_f32 v[0:1], v[58:59], v[0:1]
	ds_read_b128 v[20:23], v74 offset:6400
	v_pk_fma_f32 v[0:1], v[60:61], v[2:3], v[0:1]
	ds_read_b32 v62, v75 offset:160
	v_add_f32_e32 v0, v0, v1
	v_pk_mul_f32 v[12:13], v[12:13], v[42:43] op_sel_hi:[1,0]
	v_pk_mul_f32 v[14:15], v[14:15], v[42:43] op_sel_hi:[1,0]
	v_add_f32_dpp v0, v0, v0 quad_perm:[1,0,3,2] row_mask:0xf bank_mask:0xf bound_ctrl:1
	v_pk_fma_f32 v[12:13], v[58:59], v[4:5], v[12:13]
	v_pk_fma_f32 v[14:15], v[60:61], v[6:7], v[14:15]
	v_pk_mul_f32 v[64:65], v[36:37], v[58:59]
	v_add_f32_dpp v0, v0, v0 quad_perm:[2,3,0,1] row_mask:0xf bank_mask:0xf bound_ctrl:1
	v_pk_fma_f32 v[64:65], v[38:39], v[60:61], v[64:65]
	ds_read_b128 v[24:27], v74 offset:6656
	v_add_f32_dpp v0, v0, v0 row_half_mirror row_mask:0xf bank_mask:0xf bound_ctrl:1
	ds_read_b128 v[28:31], v74 offset:6912
	ds_read_b128 v[32:35], v74 offset:7168
	v_add_f32_dpp v0, v0, v0 row_mirror row_mask:0xf bank_mask:0xf bound_ctrl:1
	ds_read_b128 v[36:39], v74 offset:7424
	v_pk_fma_f32 v[58:59], v[8:9], v[0:1], v[12:13] op_sel_hi:[1,0,1]
	v_pk_fma_f32 v[60:61], v[10:11], v[0:1], v[14:15] op_sel_hi:[1,0,1]
	v_add_f32_e32 v64, v64, v65
	ds_write_b32 v76, v64 offset:1536
	s_waitcnt lgkmcnt(2)
	v_pk_mul_f32 v[20:21], v[58:59], v[20:21]
	ds_read_b128 v[0:3], v74 offset:7680
	v_pk_fma_f32 v[20:21], v[60:61], v[22:23], v[20:21]
	ds_read_b32 v42, v75 offset:192
	v_add_f32_e32 v20, v20, v21
	v_pk_mul_f32 v[32:33], v[32:33], v[62:63] op_sel_hi:[1,0]
	v_pk_mul_f32 v[34:35], v[34:35], v[62:63] op_sel_hi:[1,0]
	v_add_f32_dpp v20, v20, v20 quad_perm:[1,0,3,2] row_mask:0xf bank_mask:0xf bound_ctrl:1
	v_pk_fma_f32 v[32:33], v[58:59], v[24:25], v[32:33]
	v_pk_fma_f32 v[34:35], v[60:61], v[26:27], v[34:35]
	v_pk_mul_f32 v[64:65], v[16:17], v[58:59]
	v_add_f32_dpp v20, v20, v20 quad_perm:[2,3,0,1] row_mask:0xf bank_mask:0xf bound_ctrl:1
	v_pk_fma_f32 v[64:65], v[18:19], v[60:61], v[64:65]
	ds_read_b128 v[4:7], v74 offset:7936
	v_add_f32_dpp v20, v20, v20 row_half_mirror row_mask:0xf bank_mask:0xf bound_ctrl:1
	ds_read_b128 v[8:11], v74 offset:8192
	ds_read_b128 v[12:15], v74 offset:8448
	v_add_f32_dpp v20, v20, v20 row_mirror row_mask:0xf bank_mask:0xf bound_ctrl:1
	ds_read_b128 v[16:19], v74 offset:8704
	v_pk_fma_f32 v[58:59], v[28:29], v[20:21], v[32:33] op_sel_hi:[1,0,1]
	v_pk_fma_f32 v[60:61], v[30:31], v[20:21], v[34:35] op_sel_hi:[1,0,1]
	v_add_f32_e32 v64, v64, v65
	ds_write_b32 v76, v64 offset:2048
	s_waitcnt lgkmcnt(2)
	v_pk_mul_f32 v[0:1], v[58:59], v[0:1]
	ds_read_b128 v[20:23], v74 offset:8960
	v_pk_fma_f32 v[0:1], v[60:61], v[2:3], v[0:1]
	ds_read_b32 v62, v75 offset:224
	v_add_f32_e32 v0, v0, v1
	v_pk_mul_f32 v[12:13], v[12:13], v[42:43] op_sel_hi:[1,0]
	v_pk_mul_f32 v[14:15], v[14:15], v[42:43] op_sel_hi:[1,0]
	v_add_f32_dpp v0, v0, v0 quad_perm:[1,0,3,2] row_mask:0xf bank_mask:0xf bound_ctrl:1
	v_pk_fma_f32 v[12:13], v[58:59], v[4:5], v[12:13]
	v_pk_fma_f32 v[14:15], v[60:61], v[6:7], v[14:15]
	v_pk_mul_f32 v[64:65], v[36:37], v[58:59]
	v_add_f32_dpp v0, v0, v0 quad_perm:[2,3,0,1] row_mask:0xf bank_mask:0xf bound_ctrl:1
	v_pk_fma_f32 v[64:65], v[38:39], v[60:61], v[64:65]
	ds_read_b128 v[24:27], v74 offset:9216
	v_add_f32_dpp v0, v0, v0 row_half_mirror row_mask:0xf bank_mask:0xf bound_ctrl:1
	ds_read_b128 v[28:31], v74 offset:9472
	ds_read_b128 v[32:35], v74 offset:9728
	v_add_f32_dpp v0, v0, v0 row_mirror row_mask:0xf bank_mask:0xf bound_ctrl:1
	ds_read_b128 v[36:39], v74 offset:9984
	v_pk_fma_f32 v[58:59], v[8:9], v[0:1], v[12:13] op_sel_hi:[1,0,1]
	v_pk_fma_f32 v[60:61], v[10:11], v[0:1], v[14:15] op_sel_hi:[1,0,1]
	v_add_f32_e32 v64, v64, v65
	ds_write_b32 v76, v64 offset:2560
	s_waitcnt lgkmcnt(2)
	v_pk_mul_f32 v[20:21], v[58:59], v[20:21]
	ds_read_b128 v[0:3], v74 offset:10240
	v_pk_fma_f32 v[20:21], v[60:61], v[22:23], v[20:21]
	ds_read_b32 v42, v75 offset:256
	v_add_f32_e32 v20, v20, v21
	v_pk_mul_f32 v[32:33], v[32:33], v[62:63] op_sel_hi:[1,0]
	v_pk_mul_f32 v[34:35], v[34:35], v[62:63] op_sel_hi:[1,0]
	v_add_f32_dpp v20, v20, v20 quad_perm:[1,0,3,2] row_mask:0xf bank_mask:0xf bound_ctrl:1
	v_pk_fma_f32 v[32:33], v[58:59], v[24:25], v[32:33]
	v_pk_fma_f32 v[34:35], v[60:61], v[26:27], v[34:35]
	v_pk_mul_f32 v[64:65], v[16:17], v[58:59]
	v_add_f32_dpp v20, v20, v20 quad_perm:[2,3,0,1] row_mask:0xf bank_mask:0xf bound_ctrl:1
	v_pk_fma_f32 v[64:65], v[18:19], v[60:61], v[64:65]
	ds_read_b128 v[4:7], v74 offset:10496
	v_add_f32_dpp v20, v20, v20 row_half_mirror row_mask:0xf bank_mask:0xf bound_ctrl:1
	ds_read_b128 v[8:11], v74 offset:10752
	ds_read_b128 v[12:15], v74 offset:11008
	v_add_f32_dpp v20, v20, v20 row_mirror row_mask:0xf bank_mask:0xf bound_ctrl:1
	ds_read_b128 v[16:19], v74 offset:11264
	v_pk_fma_f32 v[58:59], v[28:29], v[20:21], v[32:33] op_sel_hi:[1,0,1]
	v_pk_fma_f32 v[60:61], v[30:31], v[20:21], v[34:35] op_sel_hi:[1,0,1]
	v_add_f32_e32 v64, v64, v65
	ds_write_b32 v76, v64 offset:3072
	s_waitcnt lgkmcnt(2)
	v_pk_mul_f32 v[0:1], v[58:59], v[0:1]
	ds_read_b128 v[20:23], v74 offset:11520
	v_pk_fma_f32 v[0:1], v[60:61], v[2:3], v[0:1]
	ds_read_b32 v62, v75 offset:288
	v_add_f32_e32 v0, v0, v1
	v_pk_mul_f32 v[12:13], v[12:13], v[42:43] op_sel_hi:[1,0]
	v_pk_mul_f32 v[14:15], v[14:15], v[42:43] op_sel_hi:[1,0]
	v_add_f32_dpp v0, v0, v0 quad_perm:[1,0,3,2] row_mask:0xf bank_mask:0xf bound_ctrl:1
	v_pk_fma_f32 v[12:13], v[58:59], v[4:5], v[12:13]
	v_pk_fma_f32 v[14:15], v[60:61], v[6:7], v[14:15]
	v_pk_mul_f32 v[64:65], v[36:37], v[58:59]
	v_add_f32_dpp v0, v0, v0 quad_perm:[2,3,0,1] row_mask:0xf bank_mask:0xf bound_ctrl:1
	v_pk_fma_f32 v[64:65], v[38:39], v[60:61], v[64:65]
	ds_read_b128 v[24:27], v74 offset:11776
	v_add_f32_dpp v0, v0, v0 row_half_mirror row_mask:0xf bank_mask:0xf bound_ctrl:1
	ds_read_b128 v[28:31], v74 offset:12032
	ds_read_b128 v[32:35], v74 offset:12288
	v_add_f32_dpp v0, v0, v0 row_mirror row_mask:0xf bank_mask:0xf bound_ctrl:1
	ds_read_b128 v[36:39], v74 offset:12544
	v_pk_fma_f32 v[58:59], v[8:9], v[0:1], v[12:13] op_sel_hi:[1,0,1]
	v_pk_fma_f32 v[60:61], v[10:11], v[0:1], v[14:15] op_sel_hi:[1,0,1]
	v_add_f32_e32 v64, v64, v65
	ds_write_b32 v76, v64 offset:3584
	s_waitcnt lgkmcnt(2)
; #define LAS __attribute__((address_space(3)))
; #define RW_LDS_WAIT(X) asm volatile("s_waitcnt lgkmcnt(0)" : "+v"(nk##X), "+v"(dd##X), "+v"(bb##X), "+v"(kp##X), "+v"(rr##X), "+v"(vv##X) :: "memory")
; DI void rwkv_scan_phase(int wv, const Params& P, LAS unsigned char* lds) {
;     ...
;                 f32x2 yacc = (f32x2){0.f, 0.f};
;                 unsigned sbt = sba, vbt = vba; LAS float* ybt = yb;
;                 RW_LDS_LOAD(A, 0); RW_LDS_WAIT(A);
; #pragma unroll 1
;                 for (int tt = 0; tt < RW_T; tt += 16) { sbt = sba + (unsigned)tt * 1280u; vbt = vba + (unsigned)tt * 32u; ybt = yb + tt * 128;
;                     RW_LDS_LOAD(B, 1); RW_STEP(A, 0); RW_LDS_WAIT(B);
;                     RW_LDS_LOAD(A, 2); RW_STEP(B, 1); RW_LDS_WAIT(A);
;                     RW_LDS_LOAD(B, 3); RW_STEP(A, 2); RW_LDS_WAIT(B);
;                     RW_LDS_LOAD(A, 4); RW_STEP(B, 3); RW_LDS_WAIT(A);
;                     RW_LDS_LOAD(B, 5); RW_STEP(A, 4); RW_LDS_WAIT(B);
;                     RW_LDS_LOAD(A, 6); RW_STEP(B, 5); RW_LDS_WAIT(A);
;                     RW_LDS_LOAD(B, 7); RW_STEP(A, 6); RW_LDS_WAIT(B);
;                     RW_LDS_LOAD(A, 8); RW_STEP(B, 7); RW_LDS_WAIT(A);
;                     RW_LDS_LOAD(B, 9); RW_STEP(A, 8); RW_LDS_WAIT(B);
;                     RW_LDS_LOAD(A, 10); RW_STEP(B, 9); RW_LDS_WAIT(A);
;                     RW_LDS_LOAD(B, 11); RW_STEP(A, 10); RW_LDS_WAIT(B);
;                     RW_LDS_LOAD(A, 12); RW_STEP(B, 11); RW_LDS_WAIT(A);
;                     RW_LDS_LOAD(B, 13); RW_STEP(A, 12); RW_LDS_WAIT(B);
;                     RW_LDS_LOAD(A, 14); RW_STEP(B, 13); RW_LDS_WAIT(A);
;                     RW_LDS_LOAD(B, 15); RW_STEP(A, 14); RW_LDS_WAIT(B);
;                     RW_LDS_LOAD(A, 16); RW_STEP(B, 15); RW_LDS_WAIT(A);
	v_pk_mul_f32 v[20:21], v[58:59], v[20:21]
	ds_read_b128 v[0:3], v74 offset:12800
	v_pk_fma_f32 v[20:21], v[60:61], v[22:23], v[20:21]
	ds_read_b32 v42, v75 offset:320
	v_add_f32_e32 v20, v20, v21
	v_pk_mul_f32 v[32:33], v[32:33], v[62:63] op_sel_hi:[1,0]
	v_pk_mul_f32 v[34:35], v[34:35], v[62:63] op_sel_hi:[1,0]
	v_add_f32_dpp v20, v20, v20 quad_perm:[1,0,3,2] row_mask:0xf bank_mask:0xf bound_ctrl:1
	v_pk_fma_f32 v[32:33], v[58:59], v[24:25], v[32:33]
	v_pk_fma_f32 v[34:35], v[60:61], v[26:27], v[34:35]
	v_pk_mul_f32 v[64:65], v[16:17], v[58:59]
	v_add_f32_dpp v20, v20, v20 quad_perm:[2,3,0,1] row_mask:0xf bank_mask:0xf bound_ctrl:1
	v_pk_fma_f32 v[64:65], v[18:19], v[60:61], v[64:65]
	ds_read_b128 v[4:7], v74 offset:13056
	v_add_f32_dpp v20, v20, v20 row_half_mirror row_mask:0xf bank_mask:0xf bound_ctrl:1
	ds_read_b128 v[8:11], v74 offset:13312
	ds_read_b128 v[12:15], v74 offset:13568
	v_add_f32_dpp v20, v20, v20 row_mirror row_mask:0xf bank_mask:0xf bound_ctrl:1
	ds_read_b128 v[16:19], v74 offset:13824
	v_pk_fma_f32 v[58:59], v[28:29], v[20:21], v[32:33] op_sel_hi:[1,0,1]
	v_pk_fma_f32 v[60:61], v[30:31], v[20:21], v[34:35] op_sel_hi:[1,0,1]
	v_add_f32_e32 v64, v64, v65
	ds_write_b32 v76, v64 offset:4096
	s_waitcnt lgkmcnt(2)
	v_pk_mul_f32 v[0:1], v[58:59], v[0:1]
	ds_read_b128 v[20:23], v74 offset:14080
	v_pk_fma_f32 v[0:1], v[60:61], v[2:3], v[0:1]
	ds_read_b32 v62, v75 offset:352
	v_add_f32_e32 v0, v0, v1
	v_pk_mul_f32 v[12:13], v[12:13], v[42:43] op_sel_hi:[1,0]
	v_pk_mul_f32 v[14:15], v[14:15], v[42:43] op_sel_hi:[1,0]
	v_add_f32_dpp v0, v0, v0 quad_perm:[1,0,3,2] row_mask:0xf bank_mask:0xf bound_ctrl:1
	v_pk_fma_f32 v[12:13], v[58:59], v[4:5], v[12:13]
	v_pk_fma_f32 v[14:15], v[60:61], v[6:7], v[14:15]
	v_pk_mul_f32 v[64:65], v[36:37], v[58:59]
	v_add_f32_dpp v0, v0, v0 quad_perm:[2,3,0,1] row_mask:0xf bank_mask:0xf bound_ctrl:1
	v_pk_fma_f32 v[64:65], v[38:39], v[60:61], v[64:65]
	ds_read_b128 v[24:27], v74 offset:14336
	v_add_f32_dpp v0, v0, v0 row_half_mirror row_mask:0xf bank_mask:0xf bound_ctrl:1
	ds_read_b128 v[28:31], v74 offset:14592
	ds_read_b128 v[32:35], v74 offset:14848
	v_add_f32_dpp v0, v0, v0 row_mirror row_mask:0xf bank_mask:0xf bound_ctrl:1
	ds_read_b128 v[36:39], v74 offset:15104
	v_pk_fma_f32 v[58:59], v[8:9], v[0:1], v[12:13] op_sel_hi:[1,0,1]
	v_pk_fma_f32 v[60:61], v[10:11], v[0:1], v[14:15] op_sel_hi:[1,0,1]
	v_add_f32_e32 v64, v64, v65
	ds_write_b32 v76, v64 offset:4608
	s_waitcnt lgkmcnt(2)
	v_pk_mul_f32 v[20:21], v[58:59], v[20:21]
	ds_read_b128 v[0:3], v74 offset:15360
	v_pk_fma_f32 v[20:21], v[60:61], v[22:23], v[20:21]
	ds_read_b32 v42, v75 offset:384
	v_add_f32_e32 v20, v20, v21
	v_pk_mul_f32 v[32:33], v[32:33], v[62:63] op_sel_hi:[1,0]
	v_pk_mul_f32 v[34:35], v[34:35], v[62:63] op_sel_hi:[1,0]
	v_add_f32_dpp v20, v20, v20 quad_perm:[1,0,3,2] row_mask:0xf bank_mask:0xf bound_ctrl:1
	v_pk_fma_f32 v[32:33], v[58:59], v[24:25], v[32:33]
	v_pk_fma_f32 v[34:35], v[60:61], v[26:27], v[34:35]
	v_pk_mul_f32 v[64:65], v[16:17], v[58:59]
	v_add_f32_dpp v20, v20, v20 quad_perm:[2,3,0,1] row_mask:0xf bank_mask:0xf bound_ctrl:1
	v_pk_fma_f32 v[64:65], v[18:19], v[60:61], v[64:65]
	ds_read_b128 v[4:7], v74 offset:15616
	v_add_f32_dpp v20, v20, v20 row_half_mirror row_mask:0xf bank_mask:0xf bound_ctrl:1
	ds_read_b128 v[8:11], v74 offset:15872
	ds_read_b128 v[12:15], v74 offset:16128
	v_add_f32_dpp v20, v20, v20 row_mirror row_mask:0xf bank_mask:0xf bound_ctrl:1
	ds_read_b128 v[16:19], v74 offset:16384
	v_pk_fma_f32 v[58:59], v[28:29], v[20:21], v[32:33] op_sel_hi:[1,0,1]
	v_pk_fma_f32 v[60:61], v[30:31], v[20:21], v[34:35] op_sel_hi:[1,0,1]
	v_add_f32_e32 v64, v64, v65
	ds_write_b32 v76, v64 offset:5120
	s_waitcnt lgkmcnt(2)
	v_pk_mul_f32 v[0:1], v[58:59], v[0:1]
	ds_read_b128 v[20:23], v74 offset:16640
	v_pk_fma_f32 v[0:1], v[60:61], v[2:3], v[0:1]
	ds_read_b32 v62, v75 offset:416
	v_add_f32_e32 v0, v0, v1
	v_pk_mul_f32 v[12:13], v[12:13], v[42:43] op_sel_hi:[1,0]
	v_pk_mul_f32 v[14:15], v[14:15], v[42:43] op_sel_hi:[1,0]
	v_add_f32_dpp v0, v0, v0 quad_perm:[1,0,3,2] row_mask:0xf bank_mask:0xf bound_ctrl:1
	v_pk_fma_f32 v[12:13], v[58:59], v[4:5], v[12:13]
	v_pk_fma_f32 v[14:15], v[60:61], v[6:7], v[14:15]
	v_pk_mul_f32 v[64:65], v[36:37], v[58:59]
	v_add_f32_dpp v0, v0, v0 quad_perm:[2,3,0,1] row_mask:0xf bank_mask:0xf bound_ctrl:1
	v_pk_fma_f32 v[64:65], v[38:39], v[60:61], v[64:65]
	ds_read_b128 v[24:27], v74 offset:16896
	v_add_f32_dpp v0, v0, v0 row_half_mirror row_mask:0xf bank_mask:0xf bound_ctrl:1
	ds_read_b128 v[28:31], v74 offset:17152
	ds_read_b128 v[32:35], v74 offset:17408
	v_add_f32_dpp v0, v0, v0 row_mirror row_mask:0xf bank_mask:0xf bound_ctrl:1
	ds_read_b128 v[36:39], v74 offset:17664
	v_pk_fma_f32 v[58:59], v[8:9], v[0:1], v[12:13] op_sel_hi:[1,0,1]
	v_pk_fma_f32 v[60:61], v[10:11], v[0:1], v[14:15] op_sel_hi:[1,0,1]
	v_add_f32_e32 v64, v64, v65
	ds_write_b32 v76, v64 offset:5632
	s_waitcnt lgkmcnt(2)
	v_pk_mul_f32 v[20:21], v[58:59], v[20:21]
	ds_read_b128 v[0:3], v74 offset:17920
	v_pk_fma_f32 v[20:21], v[60:61], v[22:23], v[20:21]
	ds_read_b32 v42, v75 offset:448
	v_add_f32_e32 v20, v20, v21
	v_pk_mul_f32 v[32:33], v[32:33], v[62:63] op_sel_hi:[1,0]
	v_pk_mul_f32 v[34:35], v[34:35], v[62:63] op_sel_hi:[1,0]
	v_add_f32_dpp v20, v20, v20 quad_perm:[1,0,3,2] row_mask:0xf bank_mask:0xf bound_ctrl:1
	v_pk_fma_f32 v[32:33], v[58:59], v[24:25], v[32:33]
	v_pk_fma_f32 v[34:35], v[60:61], v[26:27], v[34:35]
	v_pk_mul_f32 v[64:65], v[16:17], v[58:59]
	v_add_f32_dpp v20, v20, v20 quad_perm:[2,3,0,1] row_mask:0xf bank_mask:0xf bound_ctrl:1
	v_pk_fma_f32 v[64:65], v[18:19], v[60:61], v[64:65]
	ds_read_b128 v[4:7], v74 offset:18176
	v_add_f32_dpp v20, v20, v20 row_half_mirror row_mask:0xf bank_mask:0xf bound_ctrl:1
	ds_read_b128 v[8:11], v74 offset:18432
	ds_read_b128 v[12:15], v74 offset:18688
	v_add_f32_dpp v20, v20, v20 row_mirror row_mask:0xf bank_mask:0xf bound_ctrl:1
	ds_read_b128 v[16:19], v74 offset:18944
	v_pk_fma_f32 v[58:59], v[28:29], v[20:21], v[32:33] op_sel_hi:[1,0,1]
	v_pk_fma_f32 v[60:61], v[30:31], v[20:21], v[34:35] op_sel_hi:[1,0,1]
	v_add_f32_e32 v64, v64, v65
	ds_write_b32 v76, v64 offset:6144
	s_waitcnt lgkmcnt(2)
; #define LAS __attribute__((address_space(3)))
; #define RW_LDS_WAIT(X) asm volatile("s_waitcnt lgkmcnt(0)" : "+v"(nk##X), "+v"(dd##X), "+v"(bb##X), "+v"(kp##X), "+v"(rr##X), "+v"(vv##X) :: "memory")
; DI void rwkv_scan_phase(int wv, const Params& P, LAS unsigned char* lds) {
;     ...
;                 f32x2 yacc = (f32x2){0.f, 0.f};
;                 unsigned sbt = sba, vbt = vba; LAS float* ybt = yb;
;                 RW_LDS_LOAD(A, 0); RW_LDS_WAIT(A);
; #pragma unroll 1
;                 for (int tt = 0; tt < RW_T; tt += 16) { sbt = sba + (unsigned)tt * 1280u; vbt = vba + (unsigned)tt * 32u; ybt = yb + tt * 128;
;                     RW_LDS_LOAD(B, 1); RW_STEP(A, 0); RW_LDS_WAIT(B);
;                     RW_LDS_LOAD(A, 2); RW_STEP(B, 1); RW_LDS_WAIT(A);
;                     RW_LDS_LOAD(B, 3); RW_STEP(A, 2); RW_LDS_WAIT(B);
;                     RW_LDS_LOAD(A, 4); RW_STEP(B, 3); RW_LDS_WAIT(A);
;                     RW_LDS_LOAD(B, 5); RW_STEP(A, 4); RW_LDS_WAIT(B);
;                     RW_LDS_LOAD(A, 6); RW_STEP(B, 5); RW_LDS_WAIT(A);
;                     RW_LDS_LOAD(B, 7); RW_STEP(A, 6); RW_LDS_WAIT(B);
;                     RW_LDS_LOAD(A, 8); RW_STEP(B, 7); RW_LDS_WAIT(A);
;                     RW_LDS_LOAD(B, 9); RW_STEP(A, 8); RW_LDS_WAIT(B);
;                     RW_LDS_LOAD(A, 10); RW_STEP(B, 9); RW_LDS_WAIT(A);
;                     RW_LDS_LOAD(B, 11); RW_STEP(A, 10); RW_LDS_WAIT(B);
;                     RW_LDS_LOAD(A, 12); RW_STEP(B, 11); RW_LDS_WAIT(A);
;                     RW_LDS_LOAD(B, 13); RW_STEP(A, 12); RW_LDS_WAIT(B);
;                     RW_LDS_LOAD(A, 14); RW_STEP(B, 13); RW_LDS_WAIT(A);
;                     RW_LDS_LOAD(B, 15); RW_STEP(A, 14); RW_LDS_WAIT(B);
;                     RW_LDS_LOAD(A, 16); RW_STEP(B, 15); RW_LDS_WAIT(A);
	v_pk_mul_f32 v[0:1], v[58:59], v[0:1]
	ds_read_b128 v[20:23], v74 offset:19200
	v_pk_fma_f32 v[0:1], v[60:61], v[2:3], v[0:1]
	ds_read_b32 v62, v75 offset:480
	v_add_f32_e32 v0, v0, v1
	v_pk_mul_f32 v[12:13], v[12:13], v[42:43] op_sel_hi:[1,0]
	v_pk_mul_f32 v[14:15], v[14:15], v[42:43] op_sel_hi:[1,0]
	v_add_f32_dpp v0, v0, v0 quad_perm:[1,0,3,2] row_mask:0xf bank_mask:0xf bound_ctrl:1
	v_pk_fma_f32 v[12:13], v[58:59], v[4:5], v[12:13]
	v_pk_fma_f32 v[14:15], v[60:61], v[6:7], v[14:15]
	v_pk_mul_f32 v[64:65], v[36:37], v[58:59]
	v_add_f32_dpp v0, v0, v0 quad_perm:[2,3,0,1] row_mask:0xf bank_mask:0xf bound_ctrl:1
	v_pk_fma_f32 v[64:65], v[38:39], v[60:61], v[64:65]
	ds_read_b128 v[24:27], v74 offset:19456
	v_add_f32_dpp v0, v0, v0 row_half_mirror row_mask:0xf bank_mask:0xf bound_ctrl:1
	ds_read_b128 v[28:31], v74 offset:19712
	ds_read_b128 v[32:35], v74 offset:19968
	v_add_f32_dpp v0, v0, v0 row_mirror row_mask:0xf bank_mask:0xf bound_ctrl:1
	ds_read_b128 v[36:39], v74 offset:20224
	v_pk_fma_f32 v[58:59], v[8:9], v[0:1], v[12:13] op_sel_hi:[1,0,1]
	v_pk_fma_f32 v[60:61], v[10:11], v[0:1], v[14:15] op_sel_hi:[1,0,1]
	v_add_f32_e32 v64, v64, v65
	ds_write_b32 v76, v64 offset:6656
	s_waitcnt lgkmcnt(2)
	v_pk_mul_f32 v[20:21], v[58:59], v[20:21]
	ds_read_b128 v[0:3], v74 offset:20480
	v_pk_fma_f32 v[20:21], v[60:61], v[22:23], v[20:21]
	ds_read_b32 v42, v75 offset:512
	v_add_f32_e32 v20, v20, v21
	v_pk_mul_f32 v[32:33], v[32:33], v[62:63] op_sel_hi:[1,0]
	v_pk_mul_f32 v[34:35], v[34:35], v[62:63] op_sel_hi:[1,0]
	v_add_f32_dpp v20, v20, v20 quad_perm:[1,0,3,2] row_mask:0xf bank_mask:0xf bound_ctrl:1
	v_pk_fma_f32 v[32:33], v[58:59], v[24:25], v[32:33]
	v_pk_fma_f32 v[34:35], v[60:61], v[26:27], v[34:35]
	v_pk_mul_f32 v[64:65], v[16:17], v[58:59]
	v_add_f32_dpp v20, v20, v20 quad_perm:[2,3,0,1] row_mask:0xf bank_mask:0xf bound_ctrl:1
	v_pk_fma_f32 v[64:65], v[18:19], v[60:61], v[64:65]
	ds_read_b128 v[4:7], v74 offset:20736
	v_add_f32_dpp v20, v20, v20 row_half_mirror row_mask:0xf bank_mask:0xf bound_ctrl:1
	ds_read_b128 v[8:11], v74 offset:20992
	ds_read_b128 v[12:15], v74 offset:21248
	v_add_f32_dpp v20, v20, v20 row_mirror row_mask:0xf bank_mask:0xf bound_ctrl:1
	ds_read_b128 v[16:19], v74 offset:21504
	v_pk_fma_f32 v[58:59], v[28:29], v[20:21], v[32:33] op_sel_hi:[1,0,1]
	v_pk_fma_f32 v[60:61], v[30:31], v[20:21], v[34:35] op_sel_hi:[1,0,1]
	v_add_f32_e32 v64, v64, v65
	ds_write_b32 v76, v64 offset:7168
	s_waitcnt lgkmcnt(2)
	v_pk_mul_f32 v[0:1], v[58:59], v[0:1]
	ds_read_b128 v[20:23], v74 offset:21760
	v_pk_fma_f32 v[0:1], v[60:61], v[2:3], v[0:1]
	ds_read_b32 v62, v75 offset:544
	v_add_f32_e32 v0, v0, v1
	v_pk_mul_f32 v[12:13], v[12:13], v[42:43] op_sel_hi:[1,0]
	v_pk_mul_f32 v[14:15], v[14:15], v[42:43] op_sel_hi:[1,0]
	v_add_f32_dpp v0, v0, v0 quad_perm:[1,0,3,2] row_mask:0xf bank_mask:0xf bound_ctrl:1
	v_pk_fma_f32 v[12:13], v[58:59], v[4:5], v[12:13]
	v_pk_fma_f32 v[14:15], v[60:61], v[6:7], v[14:15]
	v_pk_mul_f32 v[64:65], v[36:37], v[58:59]
	v_add_f32_dpp v0, v0, v0 quad_perm:[2,3,0,1] row_mask:0xf bank_mask:0xf bound_ctrl:1
	v_pk_fma_f32 v[64:65], v[38:39], v[60:61], v[64:65]
	ds_read_b128 v[24:27], v74 offset:22016
	v_add_f32_dpp v0, v0, v0 row_half_mirror row_mask:0xf bank_mask:0xf bound_ctrl:1
	ds_read_b128 v[28:31], v74 offset:22272
	ds_read_b128 v[32:35], v74 offset:22528
	v_add_f32_dpp v0, v0, v0 row_mirror row_mask:0xf bank_mask:0xf bound_ctrl:1
	ds_read_b128 v[36:39], v74 offset:22784
	v_pk_fma_f32 v[58:59], v[8:9], v[0:1], v[12:13] op_sel_hi:[1,0,1]
	v_pk_fma_f32 v[60:61], v[10:11], v[0:1], v[14:15] op_sel_hi:[1,0,1]
	v_add_f32_e32 v64, v64, v65
	ds_write_b32 v76, v64 offset:7680
	s_waitcnt lgkmcnt(2)
	v_pk_mul_f32 v[20:21], v[58:59], v[20:21]
	ds_read_b128 v[0:3], v74 offset:23040
	v_pk_fma_f32 v[20:21], v[60:61], v[22:23], v[20:21]
	ds_read_b32 v42, v75 offset:576
	v_add_f32_e32 v20, v20, v21
	v_pk_mul_f32 v[32:33], v[32:33], v[62:63] op_sel_hi:[1,0]
	v_pk_mul_f32 v[34:35], v[34:35], v[62:63] op_sel_hi:[1,0]
	v_add_f32_dpp v20, v20, v20 quad_perm:[1,0,3,2] row_mask:0xf bank_mask:0xf bound_ctrl:1
	v_pk_fma_f32 v[32:33], v[58:59], v[24:25], v[32:33]
	v_pk_fma_f32 v[34:35], v[60:61], v[26:27], v[34:35]
	v_pk_mul_f32 v[64:65], v[16:17], v[58:59]
	v_add_f32_dpp v20, v20, v20 quad_perm:[2,3,0,1] row_mask:0xf bank_mask:0xf bound_ctrl:1
	v_pk_fma_f32 v[64:65], v[18:19], v[60:61], v[64:65]
	ds_read_b128 v[4:7], v74 offset:23296
	v_add_f32_dpp v20, v20, v20 row_half_mirror row_mask:0xf bank_mask:0xf bound_ctrl:1
	ds_read_b128 v[8:11], v74 offset:23552
	ds_read_b128 v[12:15], v74 offset:23808
	v_add_f32_dpp v20, v20, v20 row_mirror row_mask:0xf bank_mask:0xf bound_ctrl:1
	ds_read_b128 v[16:19], v74 offset:24064
	v_pk_fma_f32 v[58:59], v[28:29], v[20:21], v[32:33] op_sel_hi:[1,0,1]
	v_pk_fma_f32 v[60:61], v[30:31], v[20:21], v[34:35] op_sel_hi:[1,0,1]
	v_add_f32_e32 v64, v64, v65
	ds_write_b32 v76, v64 offset:8192
	s_waitcnt lgkmcnt(2)
	v_pk_mul_f32 v[0:1], v[58:59], v[0:1]
	ds_read_b128 v[20:23], v74 offset:24320
	v_pk_fma_f32 v[0:1], v[60:61], v[2:3], v[0:1]
	ds_read_b32 v62, v75 offset:608
	v_add_f32_e32 v0, v0, v1
	v_pk_mul_f32 v[12:13], v[12:13], v[42:43] op_sel_hi:[1,0]
	v_pk_mul_f32 v[14:15], v[14:15], v[42:43] op_sel_hi:[1,0]
	v_add_f32_dpp v0, v0, v0 quad_perm:[1,0,3,2] row_mask:0xf bank_mask:0xf bound_ctrl:1
	v_pk_fma_f32 v[12:13], v[58:59], v[4:5], v[12:13]
	v_pk_fma_f32 v[14:15], v[60:61], v[6:7], v[14:15]
	v_pk_mul_f32 v[64:65], v[36:37], v[58:59]
	v_add_f32_dpp v0, v0, v0 quad_perm:[2,3,0,1] row_mask:0xf bank_mask:0xf bound_ctrl:1
	v_pk_fma_f32 v[64:65], v[38:39], v[60:61], v[64:65]
	ds_read_b128 v[24:27], v74 offset:24576
	v_add_f32_dpp v0, v0, v0 row_half_mirror row_mask:0xf bank_mask:0xf bound_ctrl:1
	ds_read_b128 v[28:31], v74 offset:24832
	ds_read_b128 v[32:35], v74 offset:25088
	v_add_f32_dpp v0, v0, v0 row_mirror row_mask:0xf bank_mask:0xf bound_ctrl:1
	ds_read_b128 v[36:39], v74 offset:25344
	v_pk_fma_f32 v[58:59], v[8:9], v[0:1], v[12:13] op_sel_hi:[1,0,1]
	v_pk_fma_f32 v[60:61], v[10:11], v[0:1], v[14:15] op_sel_hi:[1,0,1]
	v_add_f32_e32 v64, v64, v65
	ds_write_b32 v76, v64 offset:8704
	s_waitcnt lgkmcnt(2)
; #define LAS __attribute__((address_space(3)))
; #define RW_LDS_WAIT(X) asm volatile("s_waitcnt lgkmcnt(0)" : "+v"(nk##X), "+v"(dd##X), "+v"(bb##X), "+v"(kp##X), "+v"(rr##X), "+v"(vv##X) :: "memory")
; DI void rwkv_scan_phase(int wv, const Params& P, LAS unsigned char* lds) {
;     ...
;                 f32x2 yacc = (f32x2){0.f, 0.f};
;                 unsigned sbt = sba, vbt = vba; LAS float* ybt = yb;
;                 RW_LDS_LOAD(A, 0); RW_LDS_WAIT(A);
; #pragma unroll 1
;                 for (int tt = 0; tt < RW_T; tt += 16) { sbt = sba + (unsigned)tt * 1280u; vbt = vba + (unsigned)tt * 32u; ybt = yb + tt * 128;
;                     RW_LDS_LOAD(B, 1); RW_STEP(A, 0); RW_LDS_WAIT(B);
;                     RW_LDS_LOAD(A, 2); RW_STEP(B, 1); RW_LDS_WAIT(A);
;                     RW_LDS_LOAD(B, 3); RW_STEP(A, 2); RW_LDS_WAIT(B);
;                     RW_LDS_LOAD(A, 4); RW_STEP(B, 3); RW_LDS_WAIT(A);
;                     RW_LDS_LOAD(B, 5); RW_STEP(A, 4); RW_LDS_WAIT(B);
;                     RW_LDS_LOAD(A, 6); RW_STEP(B, 5); RW_LDS_WAIT(A);
;                     RW_LDS_LOAD(B, 7); RW_STEP(A, 6); RW_LDS_WAIT(B);
;                     RW_LDS_LOAD(A, 8); RW_STEP(B, 7); RW_LDS_WAIT(A);
;                     RW_LDS_LOAD(B, 9); RW_STEP(A, 8); RW_LDS_WAIT(B);
;                     RW_LDS_LOAD(A, 10); RW_STEP(B, 9); RW_LDS_WAIT(A);
;                     RW_LDS_LOAD(B, 11); RW_STEP(A, 10); RW_LDS_WAIT(B);
;                     RW_LDS_LOAD(A, 12); RW_STEP(B, 11); RW_LDS_WAIT(A);
;                     RW_LDS_LOAD(B, 13); RW_STEP(A, 12); RW_LDS_WAIT(B);
;                     RW_LDS_LOAD(A, 14); RW_STEP(B, 13); RW_LDS_WAIT(A);
;                     RW_LDS_LOAD(B, 15); RW_STEP(A, 14); RW_LDS_WAIT(B);
;                     RW_LDS_LOAD(A, 16); RW_STEP(B, 15); RW_LDS_WAIT(A);
	v_pk_mul_f32 v[20:21], v[58:59], v[20:21]
	ds_read_b128 v[0:3], v74 offset:25600
	v_pk_fma_f32 v[20:21], v[60:61], v[22:23], v[20:21]
	ds_read_b32 v42, v75 offset:640
	v_add_f32_e32 v20, v20, v21
	v_pk_mul_f32 v[32:33], v[32:33], v[62:63] op_sel_hi:[1,0]
	v_pk_mul_f32 v[34:35], v[34:35], v[62:63] op_sel_hi:[1,0]
	v_add_f32_dpp v20, v20, v20 quad_perm:[1,0,3,2] row_mask:0xf bank_mask:0xf bound_ctrl:1
	v_pk_fma_f32 v[32:33], v[58:59], v[24:25], v[32:33]
	v_pk_fma_f32 v[34:35], v[60:61], v[26:27], v[34:35]
	v_pk_mul_f32 v[64:65], v[16:17], v[58:59]
	v_add_f32_dpp v20, v20, v20 quad_perm:[2,3,0,1] row_mask:0xf bank_mask:0xf bound_ctrl:1
	v_pk_fma_f32 v[64:65], v[18:19], v[60:61], v[64:65]
	ds_read_b128 v[4:7], v74 offset:25856
	v_add_f32_dpp v20, v20, v20 row_half_mirror row_mask:0xf bank_mask:0xf bound_ctrl:1
	ds_read_b128 v[8:11], v74 offset:26112
	ds_read_b128 v[12:15], v74 offset:26368
	v_add_f32_dpp v20, v20, v20 row_mirror row_mask:0xf bank_mask:0xf bound_ctrl:1
	ds_read_b128 v[16:19], v74 offset:26624
	v_pk_fma_f32 v[58:59], v[28:29], v[20:21], v[32:33] op_sel_hi:[1,0,1]
	v_pk_fma_f32 v[60:61], v[30:31], v[20:21], v[34:35] op_sel_hi:[1,0,1]
	v_add_f32_e32 v64, v64, v65
	ds_write_b32 v76, v64 offset:9216
	s_waitcnt lgkmcnt(2)
	v_pk_mul_f32 v[0:1], v[58:59], v[0:1]
	ds_read_b128 v[20:23], v74 offset:26880
	v_pk_fma_f32 v[0:1], v[60:61], v[2:3], v[0:1]
	ds_read_b32 v62, v75 offset:672
	v_add_f32_e32 v0, v0, v1
	v_pk_mul_f32 v[12:13], v[12:13], v[42:43] op_sel_hi:[1,0]
	v_pk_mul_f32 v[14:15], v[14:15], v[42:43] op_sel_hi:[1,0]
	v_add_f32_dpp v0, v0, v0 quad_perm:[1,0,3,2] row_mask:0xf bank_mask:0xf bound_ctrl:1
	v_pk_fma_f32 v[12:13], v[58:59], v[4:5], v[12:13]
	v_pk_fma_f32 v[14:15], v[60:61], v[6:7], v[14:15]
	v_pk_mul_f32 v[64:65], v[36:37], v[58:59]
	v_add_f32_dpp v0, v0, v0 quad_perm:[2,3,0,1] row_mask:0xf bank_mask:0xf bound_ctrl:1
	v_pk_fma_f32 v[64:65], v[38:39], v[60:61], v[64:65]
	ds_read_b128 v[24:27], v74 offset:27136
	v_add_f32_dpp v0, v0, v0 row_half_mirror row_mask:0xf bank_mask:0xf bound_ctrl:1
	ds_read_b128 v[28:31], v74 offset:27392
	ds_read_b128 v[32:35], v74 offset:27648
	v_add_f32_dpp v0, v0, v0 row_mirror row_mask:0xf bank_mask:0xf bound_ctrl:1
	ds_read_b128 v[36:39], v74 offset:27904
	v_pk_fma_f32 v[58:59], v[8:9], v[0:1], v[12:13] op_sel_hi:[1,0,1]
	v_pk_fma_f32 v[60:61], v[10:11], v[0:1], v[14:15] op_sel_hi:[1,0,1]
	v_add_f32_e32 v64, v64, v65
	ds_write_b32 v76, v64 offset:9728
	s_waitcnt lgkmcnt(2)
	v_pk_mul_f32 v[20:21], v[58:59], v[20:21]
	ds_read_b128 v[0:3], v74 offset:28160
	v_pk_fma_f32 v[20:21], v[60:61], v[22:23], v[20:21]
	ds_read_b32 v42, v75 offset:704
	v_add_f32_e32 v20, v20, v21
	v_pk_mul_f32 v[32:33], v[32:33], v[62:63] op_sel_hi:[1,0]
	v_pk_mul_f32 v[34:35], v[34:35], v[62:63] op_sel_hi:[1,0]
	v_add_f32_dpp v20, v20, v20 quad_perm:[1,0,3,2] row_mask:0xf bank_mask:0xf bound_ctrl:1
	v_pk_fma_f32 v[32:33], v[58:59], v[24:25], v[32:33]
	v_pk_fma_f32 v[34:35], v[60:61], v[26:27], v[34:35]
	v_pk_mul_f32 v[64:65], v[16:17], v[58:59]
	v_add_f32_dpp v20, v20, v20 quad_perm:[2,3,0,1] row_mask:0xf bank_mask:0xf bound_ctrl:1
	v_pk_fma_f32 v[64:65], v[18:19], v[60:61], v[64:65]
	ds_read_b128 v[4:7], v74 offset:28416
	v_add_f32_dpp v20, v20, v20 row_half_mirror row_mask:0xf bank_mask:0xf bound_ctrl:1
	ds_read_b128 v[8:11], v74 offset:28672
	ds_read_b128 v[12:15], v74 offset:28928
	v_add_f32_dpp v20, v20, v20 row_mirror row_mask:0xf bank_mask:0xf bound_ctrl:1
	ds_read_b128 v[16:19], v74 offset:29184
	v_pk_fma_f32 v[58:59], v[28:29], v[20:21], v[32:33] op_sel_hi:[1,0,1]
	v_pk_fma_f32 v[60:61], v[30:31], v[20:21], v[34:35] op_sel_hi:[1,0,1]
	v_add_f32_e32 v64, v64, v65
	ds_write_b32 v76, v64 offset:10240
	s_waitcnt lgkmcnt(2)
	v_pk_mul_f32 v[0:1], v[58:59], v[0:1]
	ds_read_b128 v[20:23], v74 offset:29440
	v_pk_fma_f32 v[0:1], v[60:61], v[2:3], v[0:1]
	ds_read_b32 v62, v75 offset:736
	v_add_f32_e32 v0, v0, v1
	v_pk_mul_f32 v[12:13], v[12:13], v[42:43] op_sel_hi:[1,0]
	v_pk_mul_f32 v[14:15], v[14:15], v[42:43] op_sel_hi:[1,0]
	v_add_f32_dpp v0, v0, v0 quad_perm:[1,0,3,2] row_mask:0xf bank_mask:0xf bound_ctrl:1
	v_pk_fma_f32 v[12:13], v[58:59], v[4:5], v[12:13]
	v_pk_fma_f32 v[14:15], v[60:61], v[6:7], v[14:15]
	v_pk_mul_f32 v[64:65], v[36:37], v[58:59]
	v_add_f32_dpp v0, v0, v0 quad_perm:[2,3,0,1] row_mask:0xf bank_mask:0xf bound_ctrl:1
	v_pk_fma_f32 v[64:65], v[38:39], v[60:61], v[64:65]
	ds_read_b128 v[24:27], v74 offset:29696
	v_add_f32_dpp v0, v0, v0 row_half_mirror row_mask:0xf bank_mask:0xf bound_ctrl:1
	ds_read_b128 v[28:31], v74 offset:29952
	ds_read_b128 v[32:35], v74 offset:30208
	v_add_f32_dpp v0, v0, v0 row_mirror row_mask:0xf bank_mask:0xf bound_ctrl:1
	ds_read_b128 v[36:39], v74 offset:30464
	v_pk_fma_f32 v[58:59], v[8:9], v[0:1], v[12:13] op_sel_hi:[1,0,1]
	v_pk_fma_f32 v[60:61], v[10:11], v[0:1], v[14:15] op_sel_hi:[1,0,1]
	v_add_f32_e32 v64, v64, v65
	ds_write_b32 v76, v64 offset:10752
	s_waitcnt lgkmcnt(2)
	v_pk_mul_f32 v[20:21], v[58:59], v[20:21]
	ds_read_b128 v[0:3], v74 offset:30720
	v_pk_fma_f32 v[20:21], v[60:61], v[22:23], v[20:21]
	ds_read_b32 v42, v75 offset:768
	v_add_f32_e32 v20, v20, v21
	v_pk_mul_f32 v[32:33], v[32:33], v[62:63] op_sel_hi:[1,0]
	v_pk_mul_f32 v[34:35], v[34:35], v[62:63] op_sel_hi:[1,0]
	v_add_f32_dpp v20, v20, v20 quad_perm:[1,0,3,2] row_mask:0xf bank_mask:0xf bound_ctrl:1
	v_pk_fma_f32 v[32:33], v[58:59], v[24:25], v[32:33]
	v_pk_fma_f32 v[34:35], v[60:61], v[26:27], v[34:35]
	v_pk_mul_f32 v[64:65], v[16:17], v[58:59]
	v_add_f32_dpp v20, v20, v20 quad_perm:[2,3,0,1] row_mask:0xf bank_mask:0xf bound_ctrl:1
	v_pk_fma_f32 v[64:65], v[18:19], v[60:61], v[64:65]
	ds_read_b128 v[4:7], v74 offset:30976
	v_add_f32_dpp v20, v20, v20 row_half_mirror row_mask:0xf bank_mask:0xf bound_ctrl:1
	ds_read_b128 v[8:11], v74 offset:31232
	ds_read_b128 v[12:15], v74 offset:31488
	v_add_f32_dpp v20, v20, v20 row_mirror row_mask:0xf bank_mask:0xf bound_ctrl:1
	ds_read_b128 v[16:19], v74 offset:31744
	v_pk_fma_f32 v[58:59], v[28:29], v[20:21], v[32:33] op_sel_hi:[1,0,1]
	v_pk_fma_f32 v[60:61], v[30:31], v[20:21], v[34:35] op_sel_hi:[1,0,1]
	v_add_f32_e32 v64, v64, v65
	ds_write_b32 v76, v64 offset:11264
	s_waitcnt lgkmcnt(2)
; #define LAS __attribute__((address_space(3)))
; #define RW_LDS_WAIT(X) asm volatile("s_waitcnt lgkmcnt(0)" : "+v"(nk##X), "+v"(dd##X), "+v"(bb##X), "+v"(kp##X), "+v"(rr##X), "+v"(vv##X) :: "memory")
; DI void rwkv_scan_phase(int wv, const Params& P, LAS unsigned char* lds) {
;     ...
;                 f32x2 yacc = (f32x2){0.f, 0.f};
;                 unsigned sbt = sba, vbt = vba; LAS float* ybt = yb;
;                 RW_LDS_LOAD(A, 0); RW_LDS_WAIT(A);
; #pragma unroll 1
;                 for (int tt = 0; tt < RW_T; tt += 16) { sbt = sba + (unsigned)tt * 1280u; vbt = vba + (unsigned)tt * 32u; ybt = yb + tt * 128;
;                     RW_LDS_LOAD(B, 1); RW_STEP(A, 0); RW_LDS_WAIT(B);
;                     RW_LDS_LOAD(A, 2); RW_STEP(B, 1); RW_LDS_WAIT(A);
;                     RW_LDS_LOAD(B, 3); RW_STEP(A, 2); RW_LDS_WAIT(B);
;                     RW_LDS_LOAD(A, 4); RW_STEP(B, 3); RW_LDS_WAIT(A);
;                     RW_LDS_LOAD(B, 5); RW_STEP(A, 4); RW_LDS_WAIT(B);
;                     RW_LDS_LOAD(A, 6); RW_STEP(B, 5); RW_LDS_WAIT(A);
;                     RW_LDS_LOAD(B, 7); RW_STEP(A, 6); RW_LDS_WAIT(B);
;                     RW_LDS_LOAD(A, 8); RW_STEP(B, 7); RW_LDS_WAIT(A);
;                     RW_LDS_LOAD(B, 9); RW_STEP(A, 8); RW_LDS_WAIT(B);
;                     RW_LDS_LOAD(A, 10); RW_STEP(B, 9); RW_LDS_WAIT(A);
;                     RW_LDS_LOAD(B, 11); RW_STEP(A, 10); RW_LDS_WAIT(B);
;                     RW_LDS_LOAD(A, 12); RW_STEP(B, 11); RW_LDS_WAIT(A);
;                     RW_LDS_LOAD(B, 13); RW_STEP(A, 12); RW_LDS_WAIT(B);
;                     RW_LDS_LOAD(A, 14); RW_STEP(B, 13); RW_LDS_WAIT(A);
;                     RW_LDS_LOAD(B, 15); RW_STEP(A, 14); RW_LDS_WAIT(B);
;                     RW_LDS_LOAD(A, 16); RW_STEP(B, 15); RW_LDS_WAIT(A);
	v_pk_mul_f32 v[0:1], v[58:59], v[0:1]
	ds_read_b128 v[20:23], v74 offset:32000
	v_pk_fma_f32 v[0:1], v[60:61], v[2:3], v[0:1]
	ds_read_b32 v62, v75 offset:800
	v_add_f32_e32 v0, v0, v1
	v_pk_mul_f32 v[12:13], v[12:13], v[42:43] op_sel_hi:[1,0]
	v_pk_mul_f32 v[14:15], v[14:15], v[42:43] op_sel_hi:[1,0]
	v_add_f32_dpp v0, v0, v0 quad_perm:[1,0,3,2] row_mask:0xf bank_mask:0xf bound_ctrl:1
	v_pk_fma_f32 v[12:13], v[58:59], v[4:5], v[12:13]
	v_pk_fma_f32 v[14:15], v[60:61], v[6:7], v[14:15]
	v_pk_mul_f32 v[64:65], v[36:37], v[58:59]
	v_add_f32_dpp v0, v0, v0 quad_perm:[2,3,0,1] row_mask:0xf bank_mask:0xf bound_ctrl:1
	v_pk_fma_f32 v[64:65], v[38:39], v[60:61], v[64:65]
	ds_read_b128 v[24:27], v74 offset:32256
	v_add_f32_dpp v0, v0, v0 row_half_mirror row_mask:0xf bank_mask:0xf bound_ctrl:1
	ds_read_b128 v[28:31], v74 offset:32512
	ds_read_b128 v[32:35], v74 offset:32768
	v_add_f32_dpp v0, v0, v0 row_mirror row_mask:0xf bank_mask:0xf bound_ctrl:1
	ds_read_b128 v[36:39], v74 offset:33024
	v_pk_fma_f32 v[58:59], v[8:9], v[0:1], v[12:13] op_sel_hi:[1,0,1]
	v_pk_fma_f32 v[60:61], v[10:11], v[0:1], v[14:15] op_sel_hi:[1,0,1]
	v_add_f32_e32 v64, v64, v65
	ds_write_b32 v76, v64 offset:11776
	s_waitcnt lgkmcnt(2)
	v_pk_mul_f32 v[20:21], v[58:59], v[20:21]
	ds_read_b128 v[0:3], v74 offset:33280
	v_pk_fma_f32 v[20:21], v[60:61], v[22:23], v[20:21]
	ds_read_b32 v42, v75 offset:832
	v_add_f32_e32 v20, v20, v21
	v_pk_mul_f32 v[32:33], v[32:33], v[62:63] op_sel_hi:[1,0]
	v_pk_mul_f32 v[34:35], v[34:35], v[62:63] op_sel_hi:[1,0]
	v_add_f32_dpp v20, v20, v20 quad_perm:[1,0,3,2] row_mask:0xf bank_mask:0xf bound_ctrl:1
	v_pk_fma_f32 v[32:33], v[58:59], v[24:25], v[32:33]
	v_pk_fma_f32 v[34:35], v[60:61], v[26:27], v[34:35]
	v_pk_mul_f32 v[64:65], v[16:17], v[58:59]
	v_add_f32_dpp v20, v20, v20 quad_perm:[2,3,0,1] row_mask:0xf bank_mask:0xf bound_ctrl:1
	v_pk_fma_f32 v[64:65], v[18:19], v[60:61], v[64:65]
	ds_read_b128 v[4:7], v74 offset:33536
	v_add_f32_dpp v20, v20, v20 row_half_mirror row_mask:0xf bank_mask:0xf bound_ctrl:1
	ds_read_b128 v[8:11], v74 offset:33792
	ds_read_b128 v[12:15], v74 offset:34048
	v_add_f32_dpp v20, v20, v20 row_mirror row_mask:0xf bank_mask:0xf bound_ctrl:1
	ds_read_b128 v[16:19], v74 offset:34304
	v_pk_fma_f32 v[58:59], v[28:29], v[20:21], v[32:33] op_sel_hi:[1,0,1]
	v_pk_fma_f32 v[60:61], v[30:31], v[20:21], v[34:35] op_sel_hi:[1,0,1]
	v_add_f32_e32 v64, v64, v65
	ds_write_b32 v76, v64 offset:12288
	s_waitcnt lgkmcnt(2)
	v_pk_mul_f32 v[0:1], v[58:59], v[0:1]
	ds_read_b128 v[20:23], v74 offset:34560
	v_pk_fma_f32 v[0:1], v[60:61], v[2:3], v[0:1]
	ds_read_b32 v62, v75 offset:864
	v_add_f32_e32 v0, v0, v1
	v_pk_mul_f32 v[12:13], v[12:13], v[42:43] op_sel_hi:[1,0]
	v_pk_mul_f32 v[14:15], v[14:15], v[42:43] op_sel_hi:[1,0]
	v_add_f32_dpp v0, v0, v0 quad_perm:[1,0,3,2] row_mask:0xf bank_mask:0xf bound_ctrl:1
	v_pk_fma_f32 v[12:13], v[58:59], v[4:5], v[12:13]
	v_pk_fma_f32 v[14:15], v[60:61], v[6:7], v[14:15]
	v_pk_mul_f32 v[64:65], v[36:37], v[58:59]
	v_add_f32_dpp v0, v0, v0 quad_perm:[2,3,0,1] row_mask:0xf bank_mask:0xf bound_ctrl:1
	v_pk_fma_f32 v[64:65], v[38:39], v[60:61], v[64:65]
	ds_read_b128 v[24:27], v74 offset:34816
	v_add_f32_dpp v0, v0, v0 row_half_mirror row_mask:0xf bank_mask:0xf bound_ctrl:1
	ds_read_b128 v[28:31], v74 offset:35072
	ds_read_b128 v[32:35], v74 offset:35328
	v_add_f32_dpp v0, v0, v0 row_mirror row_mask:0xf bank_mask:0xf bound_ctrl:1
	ds_read_b128 v[36:39], v74 offset:35584
	v_pk_fma_f32 v[58:59], v[8:9], v[0:1], v[12:13] op_sel_hi:[1,0,1]
	v_pk_fma_f32 v[60:61], v[10:11], v[0:1], v[14:15] op_sel_hi:[1,0,1]
	v_add_f32_e32 v64, v64, v65
	ds_write_b32 v76, v64 offset:12800
	s_waitcnt lgkmcnt(2)
	v_pk_mul_f32 v[20:21], v[58:59], v[20:21]
	ds_read_b128 v[0:3], v74 offset:35840
	v_pk_fma_f32 v[20:21], v[60:61], v[22:23], v[20:21]
	ds_read_b32 v42, v75 offset:896
	v_add_f32_e32 v20, v20, v21
	v_pk_mul_f32 v[32:33], v[32:33], v[62:63] op_sel_hi:[1,0]
	v_pk_mul_f32 v[34:35], v[34:35], v[62:63] op_sel_hi:[1,0]
	v_add_f32_dpp v20, v20, v20 quad_perm:[1,0,3,2] row_mask:0xf bank_mask:0xf bound_ctrl:1
	v_pk_fma_f32 v[32:33], v[58:59], v[24:25], v[32:33]
	v_pk_fma_f32 v[34:35], v[60:61], v[26:27], v[34:35]
	v_pk_mul_f32 v[64:65], v[16:17], v[58:59]
	v_add_f32_dpp v20, v20, v20 quad_perm:[2,3,0,1] row_mask:0xf bank_mask:0xf bound_ctrl:1
	v_pk_fma_f32 v[64:65], v[18:19], v[60:61], v[64:65]
	ds_read_b128 v[4:7], v74 offset:36096
	v_add_f32_dpp v20, v20, v20 row_half_mirror row_mask:0xf bank_mask:0xf bound_ctrl:1
	ds_read_b128 v[8:11], v74 offset:36352
	ds_read_b128 v[12:15], v74 offset:36608
	v_add_f32_dpp v20, v20, v20 row_mirror row_mask:0xf bank_mask:0xf bound_ctrl:1
	ds_read_b128 v[16:19], v74 offset:36864
	v_pk_fma_f32 v[58:59], v[28:29], v[20:21], v[32:33] op_sel_hi:[1,0,1]
	v_pk_fma_f32 v[60:61], v[30:31], v[20:21], v[34:35] op_sel_hi:[1,0,1]
	v_add_f32_e32 v64, v64, v65
	ds_write_b32 v76, v64 offset:13312
	s_waitcnt lgkmcnt(2)
; #define LAS __attribute__((address_space(3)))
; #define RW_LDS_WAIT(X) asm volatile("s_waitcnt lgkmcnt(0)" : "+v"(nk##X), "+v"(dd##X), "+v"(bb##X), "+v"(kp##X), "+v"(rr##X), "+v"(vv##X) :: "memory")
; DI void rwkv_scan_phase(int wv, const Params& P, LAS unsigned char* lds) {
;     ...
;                 f32x2 yacc = (f32x2){0.f, 0.f};
;                 unsigned sbt = sba, vbt = vba; LAS float* ybt = yb;
;                 RW_LDS_LOAD(A, 0); RW_LDS_WAIT(A);
; #pragma unroll 1
;                 for (int tt = 0; tt < RW_T; tt += 16) { sbt = sba + (unsigned)tt * 1280u; vbt = vba + (unsigned)tt * 32u; ybt = yb + tt * 128;
;                     RW_LDS_LOAD(B, 1); RW_STEP(A, 0); RW_LDS_WAIT(B);
;                     RW_LDS_LOAD(A, 2); RW_STEP(B, 1); RW_LDS_WAIT(A);
;                     RW_LDS_LOAD(B, 3); RW_STEP(A, 2); RW_LDS_WAIT(B);
;                     RW_LDS_LOAD(A, 4); RW_STEP(B, 3); RW_LDS_WAIT(A);
;                     RW_LDS_LOAD(B, 5); RW_STEP(A, 4); RW_LDS_WAIT(B);
;                     RW_LDS_LOAD(A, 6); RW_STEP(B, 5); RW_LDS_WAIT(A);
;                     RW_LDS_LOAD(B, 7); RW_STEP(A, 6); RW_LDS_WAIT(B);
;                     RW_LDS_LOAD(A, 8); RW_STEP(B, 7); RW_LDS_WAIT(A);
;                     RW_LDS_LOAD(B, 9); RW_STEP(A, 8); RW_LDS_WAIT(B);
;                     RW_LDS_LOAD(A, 10); RW_STEP(B, 9); RW_LDS_WAIT(A);
;                     RW_LDS_LOAD(B, 11); RW_STEP(A, 10); RW_LDS_WAIT(B);
;                     RW_LDS_LOAD(A, 12); RW_STEP(B, 11); RW_LDS_WAIT(A);
;                     RW_LDS_LOAD(B, 13); RW_STEP(A, 12); RW_LDS_WAIT(B);
;                     RW_LDS_LOAD(A, 14); RW_STEP(B, 13); RW_LDS_WAIT(A);
;                     RW_LDS_LOAD(B, 15); RW_STEP(A, 14); RW_LDS_WAIT(B);
;                     RW_LDS_LOAD(A, 16); RW_STEP(B, 15); RW_LDS_WAIT(A);
;                 }
;                 yb[(RW_T - 1) * 128] = yacc[0] + yacc[1];
;     ...
;                 __syncthreads();
	v_pk_mul_f32 v[0:1], v[58:59], v[0:1]
	ds_read_b128 v[20:23], v74 offset:37120
	v_pk_fma_f32 v[0:1], v[60:61], v[2:3], v[0:1]
	ds_read_b32 v62, v75 offset:928
	v_add_f32_e32 v0, v0, v1
	v_pk_mul_f32 v[12:13], v[12:13], v[42:43] op_sel_hi:[1,0]
	v_pk_mul_f32 v[14:15], v[14:15], v[42:43] op_sel_hi:[1,0]
	v_add_f32_dpp v0, v0, v0 quad_perm:[1,0,3,2] row_mask:0xf bank_mask:0xf bound_ctrl:1
	v_pk_fma_f32 v[12:13], v[58:59], v[4:5], v[12:13]
	v_pk_fma_f32 v[14:15], v[60:61], v[6:7], v[14:15]
	v_pk_mul_f32 v[64:65], v[36:37], v[58:59]
	v_add_f32_dpp v0, v0, v0 quad_perm:[2,3,0,1] row_mask:0xf bank_mask:0xf bound_ctrl:1
	v_pk_fma_f32 v[64:65], v[38:39], v[60:61], v[64:65]
	ds_read_b128 v[24:27], v74 offset:37376
	v_add_f32_dpp v0, v0, v0 row_half_mirror row_mask:0xf bank_mask:0xf bound_ctrl:1
	ds_read_b128 v[28:31], v74 offset:37632
	ds_read_b128 v[32:35], v74 offset:37888
	v_add_f32_dpp v0, v0, v0 row_mirror row_mask:0xf bank_mask:0xf bound_ctrl:1
	ds_read_b128 v[36:39], v74 offset:38144
	v_pk_fma_f32 v[58:59], v[8:9], v[0:1], v[12:13] op_sel_hi:[1,0,1]
	v_pk_fma_f32 v[60:61], v[10:11], v[0:1], v[14:15] op_sel_hi:[1,0,1]
	v_add_f32_e32 v64, v64, v65
	ds_write_b32 v76, v64 offset:13824
	s_waitcnt lgkmcnt(2)
	v_pk_mul_f32 v[20:21], v[58:59], v[20:21]
	ds_read_b128 v[0:3], v74 offset:38400
	v_pk_fma_f32 v[20:21], v[60:61], v[22:23], v[20:21]
	ds_read_b32 v42, v75 offset:960
	v_add_f32_e32 v20, v20, v21
	v_pk_mul_f32 v[32:33], v[32:33], v[62:63] op_sel_hi:[1,0]
	v_pk_mul_f32 v[34:35], v[34:35], v[62:63] op_sel_hi:[1,0]
	v_add_f32_dpp v20, v20, v20 quad_perm:[1,0,3,2] row_mask:0xf bank_mask:0xf bound_ctrl:1
	v_pk_fma_f32 v[32:33], v[58:59], v[24:25], v[32:33]
	v_pk_fma_f32 v[34:35], v[60:61], v[26:27], v[34:35]
	v_pk_mul_f32 v[64:65], v[16:17], v[58:59]
	v_add_f32_dpp v20, v20, v20 quad_perm:[2,3,0,1] row_mask:0xf bank_mask:0xf bound_ctrl:1
	v_pk_fma_f32 v[64:65], v[18:19], v[60:61], v[64:65]
	ds_read_b128 v[4:7], v74 offset:38656
	v_add_f32_dpp v20, v20, v20 row_half_mirror row_mask:0xf bank_mask:0xf bound_ctrl:1
	ds_read_b128 v[8:11], v74 offset:38912
	ds_read_b128 v[12:15], v74 offset:39168
	v_add_f32_dpp v20, v20, v20 row_mirror row_mask:0xf bank_mask:0xf bound_ctrl:1
	ds_read_b128 v[16:19], v74 offset:39424
	v_pk_fma_f32 v[58:59], v[28:29], v[20:21], v[32:33] op_sel_hi:[1,0,1]
	v_pk_fma_f32 v[60:61], v[30:31], v[20:21], v[34:35] op_sel_hi:[1,0,1]
	v_add_f32_e32 v64, v64, v65
	ds_write_b32 v76, v64 offset:14336
	s_waitcnt lgkmcnt(2)
	v_pk_mul_f32 v[0:1], v[58:59], v[0:1]
	ds_read_b128 v[20:23], v74 offset:39680
	v_pk_fma_f32 v[0:1], v[60:61], v[2:3], v[0:1]
	ds_read_b32 v62, v75 offset:992
	v_add_f32_e32 v0, v0, v1
	v_pk_mul_f32 v[12:13], v[12:13], v[42:43] op_sel_hi:[1,0]
	v_pk_mul_f32 v[14:15], v[14:15], v[42:43] op_sel_hi:[1,0]
	v_add_f32_dpp v0, v0, v0 quad_perm:[1,0,3,2] row_mask:0xf bank_mask:0xf bound_ctrl:1
	v_pk_fma_f32 v[12:13], v[58:59], v[4:5], v[12:13]
	v_pk_fma_f32 v[14:15], v[60:61], v[6:7], v[14:15]
	v_pk_mul_f32 v[64:65], v[36:37], v[58:59]
	v_add_f32_dpp v0, v0, v0 quad_perm:[2,3,0,1] row_mask:0xf bank_mask:0xf bound_ctrl:1
	v_pk_fma_f32 v[64:65], v[38:39], v[60:61], v[64:65]
	ds_read_b128 v[24:27], v74 offset:39936
	v_add_f32_dpp v0, v0, v0 row_half_mirror row_mask:0xf bank_mask:0xf bound_ctrl:1
	ds_read_b128 v[28:31], v74 offset:40192
	ds_read_b128 v[32:35], v74 offset:40448
	v_add_f32_dpp v0, v0, v0 row_mirror row_mask:0xf bank_mask:0xf bound_ctrl:1
	ds_read_b128 v[36:39], v74 offset:40704
	v_pk_fma_f32 v[58:59], v[8:9], v[0:1], v[12:13] op_sel_hi:[1,0,1]
	v_pk_fma_f32 v[60:61], v[10:11], v[0:1], v[14:15] op_sel_hi:[1,0,1]
	v_add_f32_e32 v64, v64, v65
	ds_write_b32 v76, v64 offset:14848
	s_waitcnt lgkmcnt(2)
	v_pk_mul_f32 v[20:21], v[58:59], v[20:21]
	v_pk_mul_f32 v[32:33], v[32:33], v[62:63] op_sel_hi:[1,0]
	v_pk_fma_f32 v[20:21], v[60:61], v[22:23], v[20:21]
	v_pk_mul_f32 v[34:35], v[34:35], v[62:63] op_sel_hi:[1,0]
	v_add_f32_e32 v20, v20, v21
	v_pk_fma_f32 v[32:33], v[58:59], v[24:25], v[32:33]
	v_pk_fma_f32 v[34:35], v[60:61], v[26:27], v[34:35]
	v_add_f32_dpp v20, v20, v20 quad_perm:[1,0,3,2] row_mask:0xf bank_mask:0xf bound_ctrl:1
	v_pk_mul_f32 v[64:65], v[16:17], v[58:59]
	s_nop 0
	v_add_f32_dpp v20, v20, v20 quad_perm:[2,3,0,1] row_mask:0xf bank_mask:0xf bound_ctrl:1
	v_pk_fma_f32 v[64:65], v[18:19], v[60:61], v[64:65]
	s_nop 0
	v_add_f32_dpp v20, v20, v20 row_half_mirror row_mask:0xf bank_mask:0xf bound_ctrl:1
	v_add_f32_e32 v64, v64, v65
	ds_write_b32 v76, v64 offset:15360
	v_add_f32_dpp v20, v20, v20 row_mirror row_mask:0xf bank_mask:0xf bound_ctrl:1
	s_nop 0
	v_pk_fma_f32 v[58:59], v[28:29], v[20:21], v[32:33] op_sel_hi:[1,0,1]
	v_pk_fma_f32 v[60:61], v[30:31], v[20:21], v[34:35] op_sel_hi:[1,0,1]
	s_waitcnt lgkmcnt(2)
	v_pk_mul_f32 v[64:65], v[36:37], v[58:59]
	s_add_i32 s47, s47, 1
	v_pk_fma_f32 v[64:65], v[38:39], v[60:61], v[64:65]
	s_cmpk_eq_i32 s47, 0x100
	v_add_f32_e32 v64, v64, v65
	ds_write_b32 v76, v64 offset:15872
	s_waitcnt lgkmcnt(0)
	s_barrier
	s_cbranch_scc0 .Lscan_chunk

; DI void rwkv_scan_phase(int wv, const Params& P, LAS unsigned char* lds) {
;     ...
;             const int ch = h * 64 + lane;
;             const float kkw = P.in[35][ch], kaw = P.in[36][ch], rkw = P.in[37][ch];
;             const int hf = lane >> 5, c2 = lane & 31, chp = h * 64 + 2 * c2;
;             const f32x2 kkw2 = *(const f32x2*)(P.in[35] + chp), kaw2 = *(const f32x2*)(P.in[36] + chp), rkw2 = *(const f32x2*)(P.in[37] + chp);
;             unsigned gk[3], ga[3], gr[3], gl[3]; float gv[3];
;     ...
;             RW_LOADG(0)
; #pragma unroll 1
;             for (int ck = -1; ck <= nck; ++ck) {
;                 {
;                     if (ck >= 1) { const LAS float* yb = ybuf + ((ck - 1) & 1) * RW_T * 128;
; #pragma unroll 2
;                         for (int it = pw; it < 64; it += 6) { const float y = row16_sum(yb[it * 64 + lane]);
;                             const float y0 = __builtin_bit_cast(float, __builtin_amdgcn_readlane(__builtin_bit_cast(int, y), 0)), y1 = __builtin_bit_cast(float, __builtin_amdgcn_readlane(__builtin_bit_cast(int, y), 16)),
;                                         y2 = __builtin_bit_cast(float, __builtin_amdgcn_readlane(__builtin_bit_cast(int, y), 32)), y3 = __builtin_bit_cast(float, __builtin_amdgcn_readlane(__builtin_bit_cast(int, y), 48));
;                             if (lane == 0) { u32x2 w; w.x = pk2(y0, y1); w.y = pk2(y2, y3); *(u32x2*)(YS + ((size_t)b * SEQ + (ck - 1) * RW_T + (it >> 1)) * 1024 + h * 64 + rg * 8 + (it & 1) * 4) = w; } } }
;                     if (ck + 1 < nck) { const int cn = ck + 1, buf = cn & 1;
; #pragma unroll
;                         for (int i = 0; i < 3; ++i) { const int pp = pw + 6 * i; if (pp < 16) { const int tt = 2 * pp + hf; const size_t row = (size_t)b * SEQ + cn * RW_T + tt;
;                             const f32x2 k = {bflo(gk[i]), bfhi(gk[i])}, a = {bflo(ga[i]), bfhi(ga[i])}, r = {bflo(gr[i]), bfhi(gr[i])};
;                             const h16x2 lh = __builtin_bit_cast(h16x2, gl[i]);
;                             const f32x2 kr = k * kkw2, kp = k * ((a - 1.f) * kaw2 + 1.f);
;                             const float sp = kr[0] * kr[0] + kr[1] * kr[1], rp = r[0] * kp[0] * rkw2[0] + r[1] * kp[1] * rkw2[1];
;                             const bool odd = lane & 1;
;                             float red = (odd ? rp : sp) + dpp_f<0xB1>(odd ? sp : rp);
.LBB0_3185:
	s_andn2_saveexec_b64 s[40:41], s[20:21]
	s_cbranch_execz .LBB0_3174
	v_readfirstlane_b32 s55, v41
	s_and_b32 s66, s55, 2
	s_cmp_lg_u32 s66, 0
	s_cbranch_scc1 .Lprod_idle
	s_lshr_b32 s66, s55, 1
	s_and_b32 s55, s55, 1
	s_or_b32 s55, s55, s66
	s_and_b32 s67, s46, 7
	s_bfe_u32 s59, s46, 0x40003
	s_lshr_b32 s60, s46, 7
	s_lshl_b32 s60, s60, 13
	s_lshl_b32 s66, s55, 3
	s_add_i32 s60, s60, s66
	v_mbcnt_lo_u32_b32 v0, -1, 0
	v_mbcnt_hi_u32_b32 v0, -1, v0
	v_and_b32_e32 v1, 31, v0
	v_lshrrev_b32_e32 v31, 5, v0
	s_lshl_b32 s61, s59, 6
	v_lshl_add_u32 v32, v1, 1, s61
	v_lshlrev_b32_e32 v33, 2, v32
	global_load_dwordx2 v[4:5], v33, s[24:25]
	global_load_dwordx2 v[6:7], v33, s[26:27]
	global_load_dwordx2 v[8:9], v33, s[38:39]
	v_add_u32_e32 v34, s60, v31
	v_lshlrev_b32_e32 v35, 11, v34
	v_lshl_add_u32 v12, v32, 1, v35
	v_add_u32_e32 v13, 0x1000, v12
	v_add_u32_e32 v14, 0x2000, v12
	v_add_u32_e32 v15, 0x3000, v12
	v_and_b32_e32 v36, 7, v0
	s_lshl_b32 s66, s67, 3
	s_add_i32 s66, s66, s61
	v_add_u32_e32 v37, s66, v36
	v_lshl_add_u32 v16, v37, 1, v35
	v_add_u32_e32 v17, 0x1000, v16
	v_add_u32_e32 v18, 0x2000, v16
	v_add_u32_e32 v19, 0x3000, v16
	s_lshl_b32 s66, s55, 3
	v_add_u32_e32 v37, s66, v31
	v_mul_u32_u24_e32 v2, 0x500, v37
	v_lshl_add_u32 v2, v1, 3, v2
	v_lshlrev_b32_e32 v3, 5, v37
	v_lshl_add_u32 v3, v1, 2, v3
	v_add_u32_e32 v3, 0x14000, v3
	s_lshl_b32 s66, s59, 2
	v_lshl_add_u32 v10, v34, 6, s66
	v_lshrrev_b32_e32 v37, 3, v0
	s_lshl_b32 s66, s55, 3
	v_add_u32_e32 v37, s66, v37
	v_lshlrev_b32_e32 v11, 9, v37
	v_lshl_add_u32 v11, v36, 6, v11
	v_add_u32_e32 v11, 0x14800, v11
	s_lshr_b32 s66, s46, 7
	s_lshl_b32 s66, s66, 13
	v_add_u32_e32 v37, s66, v37
	v_lshlrev_b32_e32 v37, 11, v37
	s_lshl_b32 s66, s67, 3
	s_add_i32 s66, s66, s61
	v_add_u32_e32 v38, s66, v36
	v_lshl_add_u32 v20, v38, 1, v37
	v_or_b32_e32 v38, s67, v1
	v_cmp_eq_u32_e64 s[42:43], 0, v38
	s_mov_b32 s57, -1
	s_mov_b32 s67, 0
	s_add_u32 s60, s28, s67
	s_addc_u32 s61, s29, 0
	global_load_dword v44, v12, s[60:61]
	global_load_dword v49, v13, s[60:61]
	global_load_dword v54, v14, s[60:61]
	global_load_dword v59, v15, s[60:61]
	s_add_u32 s60, s34, s67
	s_addc_u32 s61, s35, 0
	global_load_dword v45, v12, s[60:61]
	global_load_dword v50, v13, s[60:61]
	global_load_dword v55, v14, s[60:61]
	global_load_dword v60, v15, s[60:61]
	s_add_u32 s60, s22, s67
	s_addc_u32 s61, s23, 0
	global_load_dword v46, v12, s[60:61]
	global_load_dword v51, v13, s[60:61]
	global_load_dword v56, v14, s[60:61]
	global_load_dword v61, v15, s[60:61]
	s_add_u32 s60, s36, s67
	s_addc_u32 s61, s37, 0
	global_load_dword v47, v12, s[60:61]
	global_load_dword v52, v13, s[60:61]
	global_load_dword v57, v14, s[60:61]
	global_load_dword v62, v15, s[60:61]
	s_add_u32 s60, s30, s67
	s_addc_u32 s61, s31, 0
	global_load_ushort v48, v16, s[60:61]
	global_load_ushort v53, v17, s[60:61]
	global_load_ushort v58, v18, s[60:61]
	global_load_ushort v63, v19, s[60:61]
.Lprod_loop:
	s_cmp_lt_i32 s57, 1
	s_cbranch_scc1 .Lprod_stage
	s_add_i32 s67, s57, -1
	s_and_b32 s67, s67, 1
	s_lshl_b32 s67, s67, 14
	v_add_u32_e32 v21, s67, v11
	ds_read_b128 v[24:27], v21
	ds_read_b128 v[28:31], v21 offset:16
	ds_read_b128 v[32:35], v21 offset:32
	ds_read_b128 v[36:39], v21 offset:48
.Lprod_stage:
	s_cmp_gt_i32 s57, 0xfe
	s_cbranch_scc1 .Lprod_flush
	s_add_i32 s67, s57, 1
	s_and_b32 s59, s67, 1
	s_mul_i32 s60, s59, 0xa000
	v_add_u32_e32 v22, s60, v2
	s_lshl_b32 s60, s59, 10
	v_add_u32_e32 v23, s60, v3
	s_lshl_b32 s60, s67, 11
	s_add_u32 s62, s50, s60
	s_addc_u32 s63, s51, 0
	s_waitcnt vmcnt(0)
	v_lshlrev_b32_e32 v64, 16, v45
	v_and_b32_e32 v65, 0xffff0000, v45
	v_pk_add_f32 v[72:73], v[64:65], -1.0 op_sel_hi:[1,0]
	v_lshlrev_b32_e32 v66, 16, v44
	v_and_b32_e32 v67, 0xffff0000, v44
	v_pk_fma_f32 v[72:73], v[6:7], v[72:73], 1.0 op_sel_hi:[1,1,0]
	v_and_b32_e32 v69, 0xffff0000, v46
	v_pk_mul_f32 v[70:71], v[4:5], v[66:67]
	v_pk_mul_f32 v[66:67], v[72:73], v[66:67]
	v_lshlrev_b32_e32 v68, 16, v46
	v_mul_f32_e32 v75, v67, v69
	v_pk_mul_f32 v[72:73], v[70:71], v[70:71]
	v_mul_f32_e32 v74, v66, v68
	v_mul_f32_e32 v75, v9, v75
	v_add_f32_e32 v76, v72, v73
	v_fmac_f32_e32 v75, v8, v74
	v_cndmask_b32_e64 v74, v75, v76, s[8:9]
	v_cndmask_b32_e64 v76, v76, v75, s[8:9]
	v_cvt_f32_f16_e32 v77, v47
	v_cvt_f32_f16_sdwa v78, v47 dst_sel:DWORD dst_unused:UNUSED_PAD src0_sel:WORD_1
	v_add_f32_dpp v76, v76, v74 quad_perm:[1,0,3,2] row_mask:0xf bank_mask:0xf bound_ctrl:1
	v_mul_f32_e32 v77, 0x3fb8aa3b, v77
	s_nop 0
	v_add_f32_dpp v76, v76, v76 quad_perm:[2,3,0,1] row_mask:0xf bank_mask:0xf bound_ctrl:1
	v_exp_f32_e32 v72, v77
	v_mul_f32_e32 v77, 0x3fb8aa3b, v78
	v_add_f32_dpp v76, v76, v76 row_ror:4 row_mask:0xf bank_mask:0xf bound_ctrl:1
	v_exp_f32_e32 v73, v77
	s_nop 0
	v_add_f32_dpp v76, v76, v76 row_ror:8 row_mask:0xf bank_mask:0xf bound_ctrl:1
	v_mov_b32_e32 v74, v76
	s_nop 1
	v_permlane16_swap_b32_e32 v76, v74
	v_add_f32_e32 v76, v76, v74
	s_nop 1
	v_mov_b32_dpp v74, v76 quad_perm:[1,0,3,2] row_mask:0xf bank_mask:0xf bound_ctrl:1
	v_cndmask_b32_e64 v75, v74, v76, s[8:9]
	v_max_f32_e32 v75, v75, v75
	v_max_f32_e32 v75, 0x179abe15, v75
	v_rsq_f32_e32 v42, v75
	v_cndmask_b32_e64 v76, v76, v74, s[8:9]
	v_lshlrev_b32_e32 v79, 16, v48
	v_pk_mul_f32 v[70:71], v[70:71], v[42:43] op_sel_hi:[1,0] neg_lo:[0,1] neg_hi:[0,1]
	ds_write_b64 v22, v[70:71] offset:0
	ds_write_b64 v22, v[72:73] offset:256
	v_pk_mul_f32 v[64:65], v[70:71], v[64:65] neg_lo:[1,0] neg_hi:[1,0]
	ds_write_b64 v22, v[66:67] offset:768
	ds_write_b64 v22, v[68:69] offset:1024
	ds_write_b64 v22, v[64:65] offset:512
	s_and_saveexec_b64 s[60:61], s[42:43]
	s_cbranch_execz .Lprod_rk_skip_0
	global_store_dword v10, v76, s[62:63]
; #define LAS __attribute__((address_space(3)))
; DI float bflo(unsigned u) { return __uint_as_float(u << 16); }
; DI float bfhi(unsigned u) { return __uint_as_float(u & 0xffff0000u); }
; template <int CTRL> DI float dpp_f(float v) { return __builtin_bit_cast(float, __builtin_amdgcn_update_dpp(0, __builtin_bit_cast(int, v), CTRL, 0xf, 0xf, true)); }
; DI void rwkv_scan_phase(int wv, const Params& P, LAS unsigned char* lds) {
;     ...
;                         for (int i = 0; i < 3; ++i) { const int pp = pw + 6 * i; if (pp < 16) { const int tt = 2 * pp + hf; const size_t row = (size_t)b * SEQ + cn * RW_T + tt;
;                             const f32x2 k = {bflo(gk[i]), bfhi(gk[i])}, a = {bflo(ga[i]), bfhi(ga[i])}, r = {bflo(gr[i]), bfhi(gr[i])};
;                             const h16x2 lh = __builtin_bit_cast(h16x2, gl[i]);
;                             const f32x2 kr = k * kkw2, kp = k * ((a - 1.f) * kaw2 + 1.f);
;                             const float sp = kr[0] * kr[0] + kr[1] * kr[1], rp = r[0] * kp[0] * rkw2[0] + r[1] * kp[1] * rkw2[1];
;                             const bool odd = lane & 1;
;                             float red = (odd ? rp : sp) + dpp_f<0xB1>(odd ? sp : rp);
;                             red += dpp_f<0x4E>(red); red += dpp_f<0x124>(red); red += dpp_f<0x128>(red);
;                             { auto x = __builtin_amdgcn_permlane16_swap(__float_as_uint(red), __float_as_uint(red), false, false); red = __uint_as_float(x[0]) + __uint_as_float(x[1]); }
;                             const float oth = dpp_f<0xB1>(red); const float ss = odd ? oth : red, rks = odd ? red : oth;
;                             const f32x2 kk = kr * __builtin_amdgcn_rsqf(fmaxf(ss, 1e-24f));
;                             LAS float* d = stg + ((buf * RW_T + tt) * 5) * 64 + 2 * c2;
;                             *(LAS f32x2*)(d) = -kk; *(LAS f32x2*)(d + 64) = (f32x2){__expf((float)lh[0]), __expf((float)lh[1])}; *(LAS f32x2*)(d + 128) = kk * a; *(LAS f32x2*)(d + 192) = kp; *(LAS f32x2*)(d + 256) = r;
;                             if (rg == 0 && c2 == 0) RK[row * 16 + h] = rks;
;                             if (c2 < 8) vst[(buf * RW_T + tt) * 8 + c2] = gv[i]; } }
.Lprod_rk_skip_0:
	s_mov_b64 exec, s[10:11]
	ds_write_b32 v23, v79
	s_mov_b64 exec, -1
	v_lshlrev_b32_e32 v64, 16, v50
	v_and_b32_e32 v65, 0xffff0000, v50
	v_pk_add_f32 v[72:73], v[64:65], -1.0 op_sel_hi:[1,0]
	v_lshlrev_b32_e32 v66, 16, v49
	v_and_b32_e32 v67, 0xffff0000, v49
	v_pk_fma_f32 v[72:73], v[6:7], v[72:73], 1.0 op_sel_hi:[1,1,0]
	v_and_b32_e32 v69, 0xffff0000, v51
	v_pk_mul_f32 v[70:71], v[4:5], v[66:67]
	v_pk_mul_f32 v[66:67], v[72:73], v[66:67]
	v_lshlrev_b32_e32 v68, 16, v51
	v_mul_f32_e32 v75, v67, v69
	v_pk_mul_f32 v[72:73], v[70:71], v[70:71]
	v_mul_f32_e32 v74, v66, v68
	v_mul_f32_e32 v75, v9, v75
	v_add_f32_e32 v76, v72, v73
	v_fmac_f32_e32 v75, v8, v74
	v_cndmask_b32_e64 v74, v75, v76, s[8:9]
	v_cndmask_b32_e64 v76, v76, v75, s[8:9]
	v_cvt_f32_f16_e32 v77, v52
	v_cvt_f32_f16_sdwa v78, v52 dst_sel:DWORD dst_unused:UNUSED_PAD src0_sel:WORD_1
	v_add_f32_dpp v76, v76, v74 quad_perm:[1,0,3,2] row_mask:0xf bank_mask:0xf bound_ctrl:1
	v_mul_f32_e32 v77, 0x3fb8aa3b, v77
	s_nop 0
	v_add_f32_dpp v76, v76, v76 quad_perm:[2,3,0,1] row_mask:0xf bank_mask:0xf bound_ctrl:1
	v_exp_f32_e32 v72, v77
	v_mul_f32_e32 v77, 0x3fb8aa3b, v78
	v_add_f32_dpp v76, v76, v76 row_ror:4 row_mask:0xf bank_mask:0xf bound_ctrl:1
	v_exp_f32_e32 v73, v77
	s_nop 0
	v_add_f32_dpp v76, v76, v76 row_ror:8 row_mask:0xf bank_mask:0xf bound_ctrl:1
	v_mov_b32_e32 v74, v76
	s_nop 1
	v_permlane16_swap_b32_e32 v76, v74
	v_add_f32_e32 v76, v76, v74
	s_nop 1
	v_mov_b32_dpp v74, v76 quad_perm:[1,0,3,2] row_mask:0xf bank_mask:0xf bound_ctrl:1
	v_cndmask_b32_e64 v75, v74, v76, s[8:9]
	v_max_f32_e32 v75, v75, v75
	v_max_f32_e32 v75, 0x179abe15, v75
	v_rsq_f32_e32 v42, v75
	v_cndmask_b32_e64 v76, v76, v74, s[8:9]
	v_lshlrev_b32_e32 v79, 16, v53
	v_pk_mul_f32 v[70:71], v[70:71], v[42:43] op_sel_hi:[1,0] neg_lo:[0,1] neg_hi:[0,1]
	ds_write_b64 v22, v[70:71] offset:2560
	ds_write_b64 v22, v[72:73] offset:2816
	v_pk_mul_f32 v[64:65], v[70:71], v[64:65] neg_lo:[1,0] neg_hi:[1,0]
	ds_write_b64 v22, v[66:67] offset:3328
	ds_write_b64 v22, v[68:69] offset:3584
	ds_write_b64 v22, v[64:65] offset:3072
	s_and_saveexec_b64 s[60:61], s[42:43]
	s_cbranch_execz .Lprod_rk_skip_1
	global_store_dword v10, v76, s[62:63] offset:128
.Lprod_rk_skip_1:
	s_mov_b64 exec, s[10:11]
	ds_write_b32 v23, v79 offset:64
	s_mov_b64 exec, -1
	v_lshlrev_b32_e32 v64, 16, v55
	v_and_b32_e32 v65, 0xffff0000, v55
	v_pk_add_f32 v[72:73], v[64:65], -1.0 op_sel_hi:[1,0]
	v_lshlrev_b32_e32 v66, 16, v54
	v_and_b32_e32 v67, 0xffff0000, v54
	v_pk_fma_f32 v[72:73], v[6:7], v[72:73], 1.0 op_sel_hi:[1,1,0]
	v_and_b32_e32 v69, 0xffff0000, v56
	v_pk_mul_f32 v[70:71], v[4:5], v[66:67]
	v_pk_mul_f32 v[66:67], v[72:73], v[66:67]
	v_lshlrev_b32_e32 v68, 16, v56
	v_mul_f32_e32 v75, v67, v69
	v_pk_mul_f32 v[72:73], v[70:71], v[70:71]
	v_mul_f32_e32 v74, v66, v68
	v_mul_f32_e32 v75, v9, v75
	v_add_f32_e32 v76, v72, v73
	v_fmac_f32_e32 v75, v8, v74
	v_cndmask_b32_e64 v74, v75, v76, s[8:9]
	v_cndmask_b32_e64 v76, v76, v75, s[8:9]
	v_cvt_f32_f16_e32 v77, v57
	v_cvt_f32_f16_sdwa v78, v57 dst_sel:DWORD dst_unused:UNUSED_PAD src0_sel:WORD_1
	v_add_f32_dpp v76, v76, v74 quad_perm:[1,0,3,2] row_mask:0xf bank_mask:0xf bound_ctrl:1
	v_mul_f32_e32 v77, 0x3fb8aa3b, v77
	s_nop 0
	v_add_f32_dpp v76, v76, v76 quad_perm:[2,3,0,1] row_mask:0xf bank_mask:0xf bound_ctrl:1
	v_exp_f32_e32 v72, v77
	v_mul_f32_e32 v77, 0x3fb8aa3b, v78
	v_add_f32_dpp v76, v76, v76 row_ror:4 row_mask:0xf bank_mask:0xf bound_ctrl:1
	v_exp_f32_e32 v73, v77
	s_nop 0
	v_add_f32_dpp v76, v76, v76 row_ror:8 row_mask:0xf bank_mask:0xf bound_ctrl:1
	v_mov_b32_e32 v74, v76
	s_nop 1
	v_permlane16_swap_b32_e32 v76, v74
	v_add_f32_e32 v76, v76, v74
	s_nop 1
	v_mov_b32_dpp v74, v76 quad_perm:[1,0,3,2] row_mask:0xf bank_mask:0xf bound_ctrl:1
	v_cndmask_b32_e64 v75, v74, v76, s[8:9]
	v_max_f32_e32 v75, v75, v75
	v_max_f32_e32 v75, 0x179abe15, v75
	v_rsq_f32_e32 v42, v75
	v_cndmask_b32_e64 v76, v76, v74, s[8:9]
	v_lshlrev_b32_e32 v79, 16, v58
	v_pk_mul_f32 v[70:71], v[70:71], v[42:43] op_sel_hi:[1,0] neg_lo:[0,1] neg_hi:[0,1]
	ds_write_b64 v22, v[70:71] offset:5120
	ds_write_b64 v22, v[72:73] offset:5376
	v_pk_mul_f32 v[64:65], v[70:71], v[64:65] neg_lo:[1,0] neg_hi:[1,0]
	ds_write_b64 v22, v[66:67] offset:5888
	ds_write_b64 v22, v[68:69] offset:6144
	ds_write_b64 v22, v[64:65] offset:5632
	s_and_saveexec_b64 s[60:61], s[42:43]
	s_cbranch_execz .Lprod_rk_skip_2
	global_store_dword v10, v76, s[62:63] offset:256
; #define LAS __attribute__((address_space(3)))
; DI void rwkv_scan_phase(int wv, const Params& P, LAS unsigned char* lds) {
;     ...
;                     if (ck >= 1) { const LAS float* yb = ybuf + ((ck - 1) & 1) * RW_T * 128;
; #pragma unroll 2
;                         for (int it = pw; it < 64; it += 6) { const float y = row16_sum(yb[it * 64 + lane]);
;                             const float y0 = __builtin_bit_cast(float, __builtin_amdgcn_readlane(__builtin_bit_cast(int, y), 0)), y1 = __builtin_bit_cast(float, __builtin_amdgcn_readlane(__builtin_bit_cast(int, y), 16)),
;                                         y2 = __builtin_bit_cast(float, __builtin_amdgcn_readlane(__builtin_bit_cast(int, y), 32)), y3 = __builtin_bit_cast(float, __builtin_amdgcn_readlane(__builtin_bit_cast(int, y), 48));
;                             if (lane == 0) { u32x2 w; w.x = pk2(y0, y1); w.y = pk2(y2, y3); *(u32x2*)(YS + ((size_t)b * SEQ + (ck - 1) * RW_T + (it >> 1)) * 1024 + h * 64 + rg * 8 + (it & 1) * 4) = w; } } }
;                     if (ck + 1 < nck) { const int cn = ck + 1, buf = cn & 1;
; #pragma unroll
;                         for (int i = 0; i < 3; ++i) { const int pp = pw + 6 * i; if (pp < 16) { const int tt = 2 * pp + hf; const size_t row = (size_t)b * SEQ + cn * RW_T + tt;
;                             const f32x2 k = {bflo(gk[i]), bfhi(gk[i])}, a = {bflo(ga[i]), bfhi(ga[i])}, r = {bflo(gr[i]), bfhi(gr[i])};
;                             const h16x2 lh = __builtin_bit_cast(h16x2, gl[i]);
;                             const f32x2 kr = k * kkw2, kp = k * ((a - 1.f) * kaw2 + 1.f);
;                             const float sp = kr[0] * kr[0] + kr[1] * kr[1], rp = r[0] * kp[0] * rkw2[0] + r[1] * kp[1] * rkw2[1];
;                             const bool odd = lane & 1;
;                             float red = (odd ? rp : sp) + dpp_f<0xB1>(odd ? sp : rp);
;                             red += dpp_f<0x4E>(red); red += dpp_f<0x124>(red); red += dpp_f<0x128>(red);
;                             { auto x = __builtin_amdgcn_permlane16_swap(__float_as_uint(red), __float_as_uint(red), false, false); red = __uint_as_float(x[0]) + __uint_as_float(x[1]); }
;                             const float oth = dpp_f<0xB1>(red); const float ss = odd ? oth : red, rks = odd ? red : oth;
;                             const f32x2 kk = kr * __builtin_amdgcn_rsqf(fmaxf(ss, 1e-24f));
.Lprod_rk_skip_2:
	s_mov_b64 exec, s[10:11]
	ds_write_b32 v23, v79 offset:128
	s_mov_b64 exec, -1
	v_lshlrev_b32_e32 v64, 16, v60
	v_and_b32_e32 v65, 0xffff0000, v60
	v_pk_add_f32 v[72:73], v[64:65], -1.0 op_sel_hi:[1,0]
	v_lshlrev_b32_e32 v66, 16, v59
	v_and_b32_e32 v67, 0xffff0000, v59
	v_pk_fma_f32 v[72:73], v[6:7], v[72:73], 1.0 op_sel_hi:[1,1,0]
	v_and_b32_e32 v69, 0xffff0000, v61
	v_pk_mul_f32 v[70:71], v[4:5], v[66:67]
	v_pk_mul_f32 v[66:67], v[72:73], v[66:67]
	v_lshlrev_b32_e32 v68, 16, v61
	v_mul_f32_e32 v75, v67, v69
	v_pk_mul_f32 v[72:73], v[70:71], v[70:71]
	v_mul_f32_e32 v74, v66, v68
	v_mul_f32_e32 v75, v9, v75
	v_add_f32_e32 v76, v72, v73
	v_fmac_f32_e32 v75, v8, v74
	v_cndmask_b32_e64 v74, v75, v76, s[8:9]
	v_cndmask_b32_e64 v76, v76, v75, s[8:9]
	v_cvt_f32_f16_e32 v77, v62
	v_cvt_f32_f16_sdwa v78, v62 dst_sel:DWORD dst_unused:UNUSED_PAD src0_sel:WORD_1
	v_add_f32_dpp v76, v76, v74 quad_perm:[1,0,3,2] row_mask:0xf bank_mask:0xf bound_ctrl:1
	v_mul_f32_e32 v77, 0x3fb8aa3b, v77
	s_nop 0
	v_add_f32_dpp v76, v76, v76 quad_perm:[2,3,0,1] row_mask:0xf bank_mask:0xf bound_ctrl:1
	v_exp_f32_e32 v72, v77
	v_mul_f32_e32 v77, 0x3fb8aa3b, v78
	v_add_f32_dpp v76, v76, v76 row_ror:4 row_mask:0xf bank_mask:0xf bound_ctrl:1
	v_exp_f32_e32 v73, v77
	s_nop 0
	v_add_f32_dpp v76, v76, v76 row_ror:8 row_mask:0xf bank_mask:0xf bound_ctrl:1
	v_mov_b32_e32 v74, v76
	s_nop 1
	v_permlane16_swap_b32_e32 v76, v74
	v_add_f32_e32 v76, v76, v74
	s_nop 1
	v_mov_b32_dpp v74, v76 quad_perm:[1,0,3,2] row_mask:0xf bank_mask:0xf bound_ctrl:1
	v_cndmask_b32_e64 v75, v74, v76, s[8:9]
	v_max_f32_e32 v75, v75, v75
	v_max_f32_e32 v75, 0x179abe15, v75
	v_rsq_f32_e32 v42, v75
	v_cndmask_b32_e64 v76, v76, v74, s[8:9]
	v_lshlrev_b32_e32 v79, 16, v63
	v_pk_mul_f32 v[70:71], v[70:71], v[42:43] op_sel_hi:[1,0] neg_lo:[0,1] neg_hi:[0,1]
	ds_write_b64 v22, v[70:71] offset:7680
	ds_write_b64 v22, v[72:73] offset:7936
	v_pk_mul_f32 v[64:65], v[70:71], v[64:65] neg_lo:[1,0] neg_hi:[1,0]
	ds_write_b64 v22, v[66:67] offset:8448
	ds_write_b64 v22, v[68:69] offset:8704
	ds_write_b64 v22, v[64:65] offset:8192
	s_and_saveexec_b64 s[60:61], s[42:43]
	s_cbranch_execz .Lprod_rk_skip_3
	global_store_dword v10, v76, s[62:63] offset:384
.Lprod_rk_skip_3:
	s_mov_b64 exec, s[10:11]
	ds_write_b32 v23, v79 offset:192
	s_mov_b64 exec, -1
	s_cmp_gt_i32 s57, 0xfd
	s_cbranch_scc1 .Lprod_flush
	s_add_i32 s67, s57, 2
	s_lshl_b32 s67, s67, 16
	s_add_u32 s60, s28, s67
	s_addc_u32 s61, s29, 0
	global_load_dword v44, v12, s[60:61]
	global_load_dword v49, v13, s[60:61]
	global_load_dword v54, v14, s[60:61]
	global_load_dword v59, v15, s[60:61]
	s_add_u32 s60, s34, s67
	s_addc_u32 s61, s35, 0
	global_load_dword v45, v12, s[60:61]
	global_load_dword v50, v13, s[60:61]
	global_load_dword v55, v14, s[60:61]
	global_load_dword v60, v15, s[60:61]
	s_add_u32 s60, s22, s67
	s_addc_u32 s61, s23, 0
	global_load_dword v46, v12, s[60:61]
	global_load_dword v51, v13, s[60:61]
	global_load_dword v56, v14, s[60:61]
	global_load_dword v61, v15, s[60:61]
	s_add_u32 s60, s36, s67
	s_addc_u32 s61, s37, 0
	global_load_dword v47, v12, s[60:61]
	global_load_dword v52, v13, s[60:61]
	global_load_dword v57, v14, s[60:61]
	global_load_dword v62, v15, s[60:61]
	s_add_u32 s60, s30, s67
	s_addc_u32 s61, s31, 0
	global_load_ushort v48, v16, s[60:61]
	global_load_ushort v53, v17, s[60:61]
	global_load_ushort v58, v18, s[60:61]
	global_load_ushort v63, v19, s[60:61]
.Lprod_flush:
	s_cmp_lt_i32 s57, 1
	s_cbranch_scc1 .Lprod_sync
	s_waitcnt lgkmcnt(0)
	v_pk_add_f32 v[24:25], v[24:25], v[26:27]
	v_pk_add_f32 v[28:29], v[28:29], v[30:31]
	v_pk_add_f32 v[32:33], v[32:33], v[34:35]
	v_pk_add_f32 v[36:37], v[36:37], v[38:39]
	v_pk_add_f32 v[24:25], v[24:25], v[28:29]
	v_pk_add_f32 v[32:33], v[32:33], v[36:37]
	s_add_i32 s67, s57, -1
	s_lshl_b32 s67, s67, 16
	v_pk_add_f32 v[24:25], v[24:25], v[32:33]
	s_add_u32 s60, s44, s67
	s_addc_u32 s61, s45, 0
	v_add_f32_e32 v24, v24, v25
	s_nop 1
	v_mov_b32_dpp v25, v24 quad_perm:[1,0,3,2] row_mask:0xf bank_mask:0xf bound_ctrl:1
	s_nop 0
	v_cvt_pk_bf16_f32 v24, v24, v25
	s_mov_b64 exec, s[8:9]
	global_store_dword v20, v24, s[60:61]
	s_mov_b64 exec, -1
.Lprod_sync:
	s_cmpk_eq_i32 s57, 0x100
	s_cbranch_scc1 .Lprod_done
	s_waitcnt lgkmcnt(0)
	s_barrier
	s_add_i32 s57, s57, 1
	s_branch .Lprod_loop
.Lprod_idle:
	s_movk_i32 s57, 0x101
.Lprod_idle_loop:
	s_barrier
	s_add_i32 s57, s57, -1
	s_cmp_lg_u32 s57, 0
	s_cbranch_scc1 .Lprod_idle_loop
.Lprod_done:
	s_branch .LBB0_3174

; __global__ void __launch_bounds__(NTHREADS, 2) mega_fwd(Params P) {
	.amdhsa_kernel _Z8mega_fwd6Params
		.amdhsa_group_segment_fixed_size 0
		.amdhsa_private_segment_fixed_size 0
		.amdhsa_kernarg_size 3696
		.amdhsa_user_sgpr_count 2
		.amdhsa_user_sgpr_dispatch_ptr 0
		.amdhsa_user_sgpr_queue_ptr 0
		.amdhsa_user_sgpr_kernarg_segment_ptr 1
		.amdhsa_user_sgpr_dispatch_id 0
		.amdhsa_user_sgpr_kernarg_preload_length 0
		.amdhsa_user_sgpr_kernarg_preload_offset 0
		.amdhsa_user_sgpr_private_segment_size 0
		.amdhsa_uses_dynamic_stack 0
		.amdhsa_enable_private_segment 0
		.amdhsa_system_sgpr_workgroup_id_x 1
		.amdhsa_system_sgpr_workgroup_id_y 0
		.amdhsa_system_sgpr_workgroup_id_z 0
		.amdhsa_system_sgpr_workgroup_info 0
		.amdhsa_system_vgpr_workitem_id 2
		.amdhsa_next_free_vgpr 254
		.amdhsa_next_free_sgpr 98
		.amdhsa_accum_offset 256
		.amdhsa_reserve_vcc 1
		.amdhsa_float_round_mode_32 0
		.amdhsa_float_round_mode_16_64 0
		.amdhsa_float_denorm_mode_32 3
		.amdhsa_float_denorm_mode_16_64 3
		.amdhsa_dx10_clamp 1
		.amdhsa_ieee_mode 1
		.amdhsa_fp16_overflow 0
		.amdhsa_tg_split 0
		.amdhsa_exception_fp_ieee_invalid_op 0
		.amdhsa_exception_fp_denorm_src 0
		.amdhsa_exception_fp_ieee_div_zero 0
		.amdhsa_exception_fp_ieee_overflow 0
		.amdhsa_exception_fp_ieee_underflow 0
		.amdhsa_exception_fp_ieee_inexact 0
		.amdhsa_exception_int_div_zero 0
	.end_amdhsa_kernel

; __global__ void __launch_bounds__(NTHREADS, 2) mega_fwd(Params P) {
amdhsa.kernels:
  - .agpr_count:     0
    .args:
      - .offset:         0
        .size:           3440
        .value_kind:     by_value
      - .offset:         3440
        .size:           4
        .value_kind:     hidden_block_count_x
      - .offset:         3444
        .size:           4
        .value_kind:     hidden_block_count_y
      - .offset:         3448
        .size:           4
        .value_kind:     hidden_block_count_z
      - .offset:         3452
        .size:           2
        .value_kind:     hidden_group_size_x
      - .offset:         3454
        .size:           2
        .value_kind:     hidden_group_size_y
      - .offset:         3456
        .size:           2
        .value_kind:     hidden_group_size_z
      - .offset:         3458
        .size:           2
        .value_kind:     hidden_remainder_x
      - .offset:         3460
        .size:           2
        .value_kind:     hidden_remainder_y
      - .offset:         3462
        .size:           2
        .value_kind:     hidden_remainder_z
      - .offset:         3480
        .size:           8
        .value_kind:     hidden_global_offset_x
      - .offset:         3488
        .size:           8
        .value_kind:     hidden_global_offset_y
      - .offset:         3496
        .size:           8
        .value_kind:     hidden_global_offset_z
      - .offset:         3504
        .size:           2
        .value_kind:     hidden_grid_dims
      - .offset:         3528
        .size:           8
        .value_kind:     hidden_multigrid_sync_arg
      - .offset:         3560
        .size:           4
        .value_kind:     hidden_dynamic_lds_size
    .group_segment_fixed_size: 0
    .kernarg_segment_align: 8
    .kernarg_segment_size: 3696
    .language:       OpenCL C
    .language_version:
      - 2
      - 0
    .max_flat_workgroup_size: 512
    .name:           _Z8mega_fwd6Params
    .private_segment_fixed_size: 0
    .sgpr_count:     104
    .sgpr_spill_count: 35
    .symbol:         _Z8mega_fwd6Params.kd
    .uniform_work_group_size: 1
    .uses_dynamic_stack: false
    .vgpr_count:     254
    .vgpr_spill_count: 0
    .wavefront_size: 64
